# M1 epilogue: straight-line plain path and batched 32-wide rotary path selected by a wave-uniform test
# speedup vs baseline: 1.0930x; 1.0093x over previous
; DI u16 f2bf(float x) { return (u16)(pack2(x, 0.f) & 0xffffu); }
; DI int crow(int i, int h) { return (i & 3) + 8 * (i >> 2) + 4 * h; }
; DI void phase_m1(const Params& p, int l, int grp, char* smem) {
;     ...
;       const bool rope32 = (cb0 == ZC_KROPE);
; #pragma unroll
;       for (int ms = 0; ms < 4; ++ms)
; #pragma unroll
;         for (int ns = 0; ns < 2; ++ns)
; #pragma unroll
;           for (int i = 0; i < 16; ++i) {
;             const int row = mt * 256 + wm * 128 + ms * 32 + crow(i, lh);
;             float v = acc[ms][ns][i] + (ns ? bias1 : bias0);
;             if (rope32 && ns == 0) {
;               const float pr = __shfl_xor(v, 16);
;               const float2 cs = t32[(row & 4095) * 16 + (lr & 15)];
;               v = (lr < 16) ? (v * cs.x - pr * cs.y) : (pr * cs.y + v * cs.x);
;             }
;             z[(size_t)row * ZW + cb0 + ns * 32 + lr] = f2bf(v);
.LBB0_645:
	s_movk_i32 s6, 0x1080
	v_cmp_eq_u32_e64 s[8:9], s6, v169
	s_nop 3
	s_cmp_eq_u64 s[8:9], 0
	s_cbranch_scc1 .Lm1_plain_fast
	s_xor_b64 s[98:99], s[8:9], exec
	s_cmp_eq_u64 s[98:99], 0
	s_cbranch_scc1 .Lm1_rope32_fast
	s_lshl_b32 s6, s39, 8
	v_lshl_add_u32 v0, v168, 7, s6
	v_lshl_or_b32 v171, v167, 2, v0
	v_and_b32_e32 v170, 15, v133
	v_cmp_gt_u32_e32 vcc, 16, v131
	s_waitcnt vmcnt(1)
	v_add_f32_e32 v136, v114, v132
	s_and_saveexec_b64 s[16:17], s[8:9]
	s_cbranch_execz .LBB0_647
	v_and_b32_e32 v134, 64, v207
	v_xor_b32_e32 v0, 16, v207
	v_add_u32_e32 v134, 64, v134
	v_cmp_lt_i32_e64 s[10:11], v0, v134
	v_lshlrev_b32_e32 v134, 4, v171
	s_mov_b32 s6, 0xf840
	v_and_or_b32 v134, v134, s6, v170
	v_lshlrev_b32_e32 v134, 3, v134
	global_load_dwordx2 v[134:135], v134, s[12:13]
	v_cndmask_b32_e64 v0, v207, v0, s[10:11]
	v_lshlrev_b32_e32 v0, 2, v0
	ds_bpermute_b32 v0, v0, v136
	s_waitcnt vmcnt(0) lgkmcnt(0)
	v_mul_f32_e32 v0, v135, v0
	v_cndmask_b32_e64 v0, v0, -v0, vcc
	v_fmac_f32_e32 v0, v136, v134
	v_mov_b32_e32 v136, v0

; DI u16 f2bf(float x) { return (u16)(pack2(x, 0.f) & 0xffffu); }
; DI int crow(int i, int h) { return (i & 3) + 8 * (i >> 2) + 4 * h; }
; DI void phase_m1(const Params& p, int l, int grp, char* smem) {
;     ...
;       for (int ms = 0; ms < 4; ++ms)
; #pragma unroll
;         for (int ns = 0; ns < 2; ++ns)
; #pragma unroll
;           for (int i = 0; i < 16; ++i) {
;             const int row = mt * 256 + wm * 128 + ms * 32 + crow(i, lh);
;             float v = acc[ms][ns][i] + (ns ? bias1 : bias0);
;             if (rope32 && ns == 0) {
;               const float pr = __shfl_xor(v, 16);
;               const float2 cs = t32[(row & 4095) * 16 + (lr & 15)];
;               v = (lr < 16) ? (v * cs.x - pr * cs.y) : (pr * cs.y + v * cs.x);
;             }
;             z[(size_t)row * ZW + cb0 + ns * 32 + lr] = f2bf(v);
.LBB0_773:
	s_or_b64 exec, exec, s[10:11]
	v_mad_i64_i32 v[134:135], s[6:7], v0, s82, v[134:135]
	v_add_f32_e32 v0, v2, v130
	v_cvt_pk_bf16_f32 v0, v0, s0
	global_store_short v[136:137], v0, off offset:64
	v_add_f32_e32 v0, v3, v130
	v_cvt_pk_bf16_f32 v0, v0, s0
	global_store_short v[138:139], v0, off offset:64
	v_add_f32_e32 v0, v4, v130
	v_cvt_pk_bf16_f32 v0, v0, s0
	global_store_short v[140:141], v0, off offset:64
	v_add_f32_e32 v0, v5, v130
	v_cvt_pk_bf16_f32 v0, v0, s0
	global_store_short v[142:143], v0, off offset:64
	v_add_f32_e32 v0, v6, v130
	v_cvt_pk_bf16_f32 v0, v0, s0
	global_store_short v[144:145], v0, off offset:64
	v_add_f32_e32 v0, v7, v130
	v_cvt_pk_bf16_f32 v0, v0, s0
	global_store_short v[146:147], v0, off offset:64
	v_add_f32_e32 v0, v8, v130
	v_cvt_pk_bf16_f32 v0, v0, s0
	global_store_short v[148:149], v0, off offset:64
	v_add_f32_e32 v0, v9, v130
	v_cvt_pk_bf16_f32 v0, v0, s0
	global_store_short v[150:151], v0, off offset:64
	v_add_f32_e32 v0, v10, v130
	v_cvt_pk_bf16_f32 v0, v0, s0
	global_store_short v[152:153], v0, off offset:64
	v_add_f32_e32 v0, v11, v130
	v_cvt_pk_bf16_f32 v0, v0, s0
	global_store_short v[154:155], v0, off offset:64
	v_add_f32_e32 v0, v12, v130
	v_cvt_pk_bf16_f32 v0, v0, s0
	global_store_short v[156:157], v0, off offset:64
	v_add_f32_e32 v0, v13, v130
	v_cvt_pk_bf16_f32 v0, v0, s0
	global_store_short v[158:159], v0, off offset:64
	v_add_f32_e32 v0, v14, v130
	v_cvt_pk_bf16_f32 v0, v0, s0
	global_store_short v[160:161], v0, off offset:64
	v_add_f32_e32 v0, v15, v130
	v_cvt_pk_bf16_f32 v0, v0, s0
	global_store_short v[162:163], v0, off offset:64
	v_add_f32_e32 v0, v16, v130
	v_cvt_pk_bf16_f32 v0, v0, s0
	global_store_short v[164:165], v0, off offset:64
	v_add_f32_e32 v0, v17, v130
	v_cvt_pk_bf16_f32 v170, v171, s0
	v_cvt_pk_bf16_f32 v0, v0, s0
	s_andn2_b64 s[24:25], s[24:25], exec
	global_store_short v[134:135], v170, off
	global_store_short v[134:135], v0, off offset:64
	s_branch .LBB0_774
.Lm1_plain_fast:
	s_lshl_b32 s6, s39, 8
	v_lshl_add_u32 v0, v168, 7, s6
	v_lshl_or_b32 v171, v167, 2, v0
	v_add_u32_e32 v134, v169, v131
	v_lshlrev_b32_e32 v134, 1, v134
	v_mad_u32_u24 v135, v171, s82, v134
	s_mov_b64 s[98:99], s[44:45]
	s_waitcnt vmcnt(0)
	v_add_f32_e32 v136, v114, v132
	v_add_f32_e32 v137, v98, v130
	v_cvt_pk_bf16_f32 v136, v136, s0
	v_cvt_pk_bf16_f32 v137, v137, s0
	global_store_short v135, v136, s[98:99]
	global_store_short v135, v137, s[98:99] offset:64
	s_add_u32 s98, s98, 0x2200
	s_addc_u32 s99, s99, 0
	v_add_f32_e32 v136, v115, v132
	v_add_f32_e32 v137, v99, v130
	v_cvt_pk_bf16_f32 v136, v136, s0
	v_cvt_pk_bf16_f32 v137, v137, s0
	global_store_short v135, v136, s[98:99]
	global_store_short v135, v137, s[98:99] offset:64
	s_add_u32 s98, s98, 0x2200
	s_addc_u32 s99, s99, 0
	v_add_f32_e32 v136, v116, v132
	v_add_f32_e32 v137, v100, v130
	v_cvt_pk_bf16_f32 v136, v136, s0
	v_cvt_pk_bf16_f32 v137, v137, s0
	global_store_short v135, v136, s[98:99]
	global_store_short v135, v137, s[98:99] offset:64
	s_add_u32 s98, s98, 0x2200
	s_addc_u32 s99, s99, 0
	v_add_f32_e32 v136, v117, v132
	v_add_f32_e32 v137, v101, v130
	v_cvt_pk_bf16_f32 v136, v136, s0
	v_cvt_pk_bf16_f32 v137, v137, s0
	global_store_short v135, v136, s[98:99]
	global_store_short v135, v137, s[98:99] offset:64
	s_add_u32 s98, s98, 0xaa00
	s_addc_u32 s99, s99, 0
	v_add_f32_e32 v136, v118, v132
	v_add_f32_e32 v137, v102, v130
	v_cvt_pk_bf16_f32 v136, v136, s0
	v_cvt_pk_bf16_f32 v137, v137, s0
	global_store_short v135, v136, s[98:99]
	global_store_short v135, v137, s[98:99] offset:64
	s_add_u32 s98, s98, 0x2200
	s_addc_u32 s99, s99, 0
	v_add_f32_e32 v136, v119, v132
	v_add_f32_e32 v137, v103, v130
	v_cvt_pk_bf16_f32 v136, v136, s0
	v_cvt_pk_bf16_f32 v137, v137, s0
	global_store_short v135, v136, s[98:99]
	global_store_short v135, v137, s[98:99] offset:64
	s_add_u32 s98, s98, 0x2200
	s_addc_u32 s99, s99, 0
	v_add_f32_e32 v136, v120, v132
	v_add_f32_e32 v137, v104, v130
	v_cvt_pk_bf16_f32 v136, v136, s0
	v_cvt_pk_bf16_f32 v137, v137, s0
	global_store_short v135, v136, s[98:99]
	global_store_short v135, v137, s[98:99] offset:64
	s_add_u32 s98, s98, 0x2200
	s_addc_u32 s99, s99, 0
	v_add_f32_e32 v136, v121, v132
	v_add_f32_e32 v137, v105, v130
	v_cvt_pk_bf16_f32 v136, v136, s0
	v_cvt_pk_bf16_f32 v137, v137, s0
	global_store_short v135, v136, s[98:99]
	global_store_short v135, v137, s[98:99] offset:64
	s_add_u32 s98, s98, 0xaa00
	s_addc_u32 s99, s99, 0
	v_add_f32_e32 v136, v122, v132
	v_add_f32_e32 v137, v106, v130
	v_cvt_pk_bf16_f32 v136, v136, s0
	v_cvt_pk_bf16_f32 v137, v137, s0
	global_store_short v135, v136, s[98:99]
	global_store_short v135, v137, s[98:99] offset:64
	s_add_u32 s98, s98, 0x2200
	s_addc_u32 s99, s99, 0
	v_add_f32_e32 v136, v123, v132
	v_add_f32_e32 v137, v107, v130
	v_cvt_pk_bf16_f32 v136, v136, s0
	v_cvt_pk_bf16_f32 v137, v137, s0
	global_store_short v135, v136, s[98:99]
	global_store_short v135, v137, s[98:99] offset:64
	s_add_u32 s98, s98, 0x2200
	s_addc_u32 s99, s99, 0
	v_add_f32_e32 v136, v124, v132
	v_add_f32_e32 v137, v108, v130
	v_cvt_pk_bf16_f32 v136, v136, s0
	v_cvt_pk_bf16_f32 v137, v137, s0
	global_store_short v135, v136, s[98:99]
	global_store_short v135, v137, s[98:99] offset:64
	s_add_u32 s98, s98, 0x2200
	s_addc_u32 s99, s99, 0
	v_add_f32_e32 v136, v125, v132
	v_add_f32_e32 v137, v109, v130
	v_cvt_pk_bf16_f32 v136, v136, s0
	v_cvt_pk_bf16_f32 v137, v137, s0
	global_store_short v135, v136, s[98:99]
	global_store_short v135, v137, s[98:99] offset:64
	s_add_u32 s98, s98, 0xaa00
	s_addc_u32 s99, s99, 0
	v_add_f32_e32 v136, v126, v132
	v_add_f32_e32 v137, v110, v130
	v_cvt_pk_bf16_f32 v136, v136, s0
; DI u16 f2bf(float x) { return (u16)(pack2(x, 0.f) & 0xffffu); }
; DI int crow(int i, int h) { return (i & 3) + 8 * (i >> 2) + 4 * h; }
; DI void phase_m1(const Params& p, int l, int grp, char* smem) {
;     ...
;       for (int ms = 0; ms < 4; ++ms)
; #pragma unroll
;         for (int ns = 0; ns < 2; ++ns)
; #pragma unroll
;           for (int i = 0; i < 16; ++i) {
;             const int row = mt * 256 + wm * 128 + ms * 32 + crow(i, lh);
;             float v = acc[ms][ns][i] + (ns ? bias1 : bias0);
;             if (rope32 && ns == 0) {
;               const float pr = __shfl_xor(v, 16);
;               const float2 cs = t32[(row & 4095) * 16 + (lr & 15)];
;               v = (lr < 16) ? (v * cs.x - pr * cs.y) : (pr * cs.y + v * cs.x);
;             }
;             z[(size_t)row * ZW + cb0 + ns * 32 + lr] = f2bf(v);
	v_cvt_pk_bf16_f32 v137, v137, s0
	global_store_short v135, v136, s[98:99]
	global_store_short v135, v137, s[98:99] offset:64
	s_add_u32 s98, s98, 0x2200
	s_addc_u32 s99, s99, 0
	v_add_f32_e32 v136, v127, v132
	v_add_f32_e32 v137, v111, v130
	v_cvt_pk_bf16_f32 v136, v136, s0
	v_cvt_pk_bf16_f32 v137, v137, s0
	global_store_short v135, v136, s[98:99]
	global_store_short v135, v137, s[98:99] offset:64
	s_add_u32 s98, s98, 0x2200
	s_addc_u32 s99, s99, 0
	v_add_f32_e32 v136, v128, v132
	v_add_f32_e32 v137, v112, v130
	v_cvt_pk_bf16_f32 v136, v136, s0
	v_cvt_pk_bf16_f32 v137, v137, s0
	global_store_short v135, v136, s[98:99]
	global_store_short v135, v137, s[98:99] offset:64
	s_add_u32 s98, s98, 0x2200
	s_addc_u32 s99, s99, 0
	v_add_f32_e32 v136, v129, v132
	v_add_f32_e32 v137, v113, v130
	v_cvt_pk_bf16_f32 v136, v136, s0
	v_cvt_pk_bf16_f32 v137, v137, s0
	global_store_short v135, v136, s[98:99]
	global_store_short v135, v137, s[98:99] offset:64
	s_add_u32 s98, s98, 0xaa00
	s_addc_u32 s99, s99, 0
	v_add_f32_e32 v136, v82, v132
	v_add_f32_e32 v137, v66, v130
	v_cvt_pk_bf16_f32 v136, v136, s0
	v_cvt_pk_bf16_f32 v137, v137, s0
	global_store_short v135, v136, s[98:99]
	global_store_short v135, v137, s[98:99] offset:64
	s_add_u32 s98, s98, 0x2200
	s_addc_u32 s99, s99, 0
	v_add_f32_e32 v136, v83, v132
	v_add_f32_e32 v137, v67, v130
	v_cvt_pk_bf16_f32 v136, v136, s0
	v_cvt_pk_bf16_f32 v137, v137, s0
	global_store_short v135, v136, s[98:99]
	global_store_short v135, v137, s[98:99] offset:64
	s_add_u32 s98, s98, 0x2200
	s_addc_u32 s99, s99, 0
	v_add_f32_e32 v136, v84, v132
	v_add_f32_e32 v137, v68, v130
	v_cvt_pk_bf16_f32 v136, v136, s0
	v_cvt_pk_bf16_f32 v137, v137, s0
	global_store_short v135, v136, s[98:99]
	global_store_short v135, v137, s[98:99] offset:64
	s_add_u32 s98, s98, 0x2200
	s_addc_u32 s99, s99, 0
	v_add_f32_e32 v136, v85, v132
	v_add_f32_e32 v137, v69, v130
	v_cvt_pk_bf16_f32 v136, v136, s0
	v_cvt_pk_bf16_f32 v137, v137, s0
	global_store_short v135, v136, s[98:99]
	global_store_short v135, v137, s[98:99] offset:64
	s_add_u32 s98, s98, 0xaa00
	s_addc_u32 s99, s99, 0
	v_add_f32_e32 v136, v86, v132
	v_add_f32_e32 v137, v70, v130
	v_cvt_pk_bf16_f32 v136, v136, s0
	v_cvt_pk_bf16_f32 v137, v137, s0
	global_store_short v135, v136, s[98:99]
	global_store_short v135, v137, s[98:99] offset:64
	s_add_u32 s98, s98, 0x2200
	s_addc_u32 s99, s99, 0
	v_add_f32_e32 v136, v87, v132
	v_add_f32_e32 v137, v71, v130
	v_cvt_pk_bf16_f32 v136, v136, s0
	v_cvt_pk_bf16_f32 v137, v137, s0
	global_store_short v135, v136, s[98:99]
	global_store_short v135, v137, s[98:99] offset:64
	s_add_u32 s98, s98, 0x2200
	s_addc_u32 s99, s99, 0
	v_add_f32_e32 v136, v88, v132
	v_add_f32_e32 v137, v72, v130
	v_cvt_pk_bf16_f32 v136, v136, s0
	v_cvt_pk_bf16_f32 v137, v137, s0
	global_store_short v135, v136, s[98:99]
	global_store_short v135, v137, s[98:99] offset:64
	s_add_u32 s98, s98, 0x2200
	s_addc_u32 s99, s99, 0
	v_add_f32_e32 v136, v89, v132
	v_add_f32_e32 v137, v73, v130
	v_cvt_pk_bf16_f32 v136, v136, s0
	v_cvt_pk_bf16_f32 v137, v137, s0
	global_store_short v135, v136, s[98:99]
	global_store_short v135, v137, s[98:99] offset:64
	s_add_u32 s98, s98, 0xaa00
	s_addc_u32 s99, s99, 0
	v_add_f32_e32 v136, v90, v132
	v_add_f32_e32 v137, v74, v130
	v_cvt_pk_bf16_f32 v136, v136, s0
	v_cvt_pk_bf16_f32 v137, v137, s0
	global_store_short v135, v136, s[98:99]
	global_store_short v135, v137, s[98:99] offset:64
	s_add_u32 s98, s98, 0x2200
	s_addc_u32 s99, s99, 0
	v_add_f32_e32 v136, v91, v132
	v_add_f32_e32 v137, v75, v130
	v_cvt_pk_bf16_f32 v136, v136, s0
	v_cvt_pk_bf16_f32 v137, v137, s0
	global_store_short v135, v136, s[98:99]
	global_store_short v135, v137, s[98:99] offset:64
	s_add_u32 s98, s98, 0x2200
	s_addc_u32 s99, s99, 0
	v_add_f32_e32 v136, v92, v132
	v_add_f32_e32 v137, v76, v130
	v_cvt_pk_bf16_f32 v136, v136, s0
	v_cvt_pk_bf16_f32 v137, v137, s0
	global_store_short v135, v136, s[98:99]
	global_store_short v135, v137, s[98:99] offset:64
	s_add_u32 s98, s98, 0x2200
	s_addc_u32 s99, s99, 0
	v_add_f32_e32 v136, v93, v132
	v_add_f32_e32 v137, v77, v130
	v_cvt_pk_bf16_f32 v136, v136, s0
	v_cvt_pk_bf16_f32 v137, v137, s0
	global_store_short v135, v136, s[98:99]
	global_store_short v135, v137, s[98:99] offset:64
	s_add_u32 s98, s98, 0xaa00
	s_addc_u32 s99, s99, 0
	v_add_f32_e32 v136, v94, v132
	v_add_f32_e32 v137, v78, v130
	v_cvt_pk_bf16_f32 v136, v136, s0
	v_cvt_pk_bf16_f32 v137, v137, s0
	global_store_short v135, v136, s[98:99]
	global_store_short v135, v137, s[98:99] offset:64
	s_add_u32 s98, s98, 0x2200
	s_addc_u32 s99, s99, 0
	v_add_f32_e32 v136, v95, v132
	v_add_f32_e32 v137, v79, v130
	v_cvt_pk_bf16_f32 v136, v136, s0
	v_cvt_pk_bf16_f32 v137, v137, s0
	global_store_short v135, v136, s[98:99]
	global_store_short v135, v137, s[98:99] offset:64
	s_add_u32 s98, s98, 0x2200
	s_addc_u32 s99, s99, 0
	v_add_f32_e32 v136, v96, v132
	v_add_f32_e32 v137, v80, v130
	v_cvt_pk_bf16_f32 v136, v136, s0
	v_cvt_pk_bf16_f32 v137, v137, s0
	global_store_short v135, v136, s[98:99]
	global_store_short v135, v137, s[98:99] offset:64
	s_add_u32 s98, s98, 0x2200
	s_addc_u32 s99, s99, 0
	v_add_f32_e32 v136, v97, v132
	v_add_f32_e32 v137, v81, v130
	v_cvt_pk_bf16_f32 v136, v136, s0
	v_cvt_pk_bf16_f32 v137, v137, s0
	global_store_short v135, v136, s[98:99]
	global_store_short v135, v137, s[98:99] offset:64
	s_add_u32 s98, s98, 0xaa00
	s_addc_u32 s99, s99, 0
	v_add_f32_e32 v136, v50, v132
	v_add_f32_e32 v137, v34, v130
	v_cvt_pk_bf16_f32 v136, v136, s0
	v_cvt_pk_bf16_f32 v137, v137, s0
	global_store_short v135, v136, s[98:99]
	global_store_short v135, v137, s[98:99] offset:64
	s_add_u32 s98, s98, 0x2200
; DI u16 f2bf(float x) { return (u16)(pack2(x, 0.f) & 0xffffu); }
; DI int crow(int i, int h) { return (i & 3) + 8 * (i >> 2) + 4 * h; }
; DI void phase_m1(const Params& p, int l, int grp, char* smem) {
;     ...
;       for (int ms = 0; ms < 4; ++ms)
; #pragma unroll
;         for (int ns = 0; ns < 2; ++ns)
; #pragma unroll
;           for (int i = 0; i < 16; ++i) {
;             const int row = mt * 256 + wm * 128 + ms * 32 + crow(i, lh);
;             float v = acc[ms][ns][i] + (ns ? bias1 : bias0);
;             if (rope32 && ns == 0) {
;               const float pr = __shfl_xor(v, 16);
;               const float2 cs = t32[(row & 4095) * 16 + (lr & 15)];
;               v = (lr < 16) ? (v * cs.x - pr * cs.y) : (pr * cs.y + v * cs.x);
;             }
;             z[(size_t)row * ZW + cb0 + ns * 32 + lr] = f2bf(v);
	s_addc_u32 s99, s99, 0
	v_add_f32_e32 v136, v51, v132
	v_add_f32_e32 v137, v35, v130
	v_cvt_pk_bf16_f32 v136, v136, s0
	v_cvt_pk_bf16_f32 v137, v137, s0
	global_store_short v135, v136, s[98:99]
	global_store_short v135, v137, s[98:99] offset:64
	s_add_u32 s98, s98, 0x2200
	s_addc_u32 s99, s99, 0
	v_add_f32_e32 v136, v52, v132
	v_add_f32_e32 v137, v36, v130
	v_cvt_pk_bf16_f32 v136, v136, s0
	v_cvt_pk_bf16_f32 v137, v137, s0
	global_store_short v135, v136, s[98:99]
	global_store_short v135, v137, s[98:99] offset:64
	s_add_u32 s98, s98, 0x2200
	s_addc_u32 s99, s99, 0
	v_add_f32_e32 v136, v53, v132
	v_add_f32_e32 v137, v37, v130
	v_cvt_pk_bf16_f32 v136, v136, s0
	v_cvt_pk_bf16_f32 v137, v137, s0
	global_store_short v135, v136, s[98:99]
	global_store_short v135, v137, s[98:99] offset:64
	s_add_u32 s98, s98, 0xaa00
	s_addc_u32 s99, s99, 0
	v_add_f32_e32 v136, v54, v132
	v_add_f32_e32 v137, v38, v130
	v_cvt_pk_bf16_f32 v136, v136, s0
	v_cvt_pk_bf16_f32 v137, v137, s0
	global_store_short v135, v136, s[98:99]
	global_store_short v135, v137, s[98:99] offset:64
	s_add_u32 s98, s98, 0x2200
	s_addc_u32 s99, s99, 0
	v_add_f32_e32 v136, v55, v132
	v_add_f32_e32 v137, v39, v130
	v_cvt_pk_bf16_f32 v136, v136, s0
	v_cvt_pk_bf16_f32 v137, v137, s0
	global_store_short v135, v136, s[98:99]
	global_store_short v135, v137, s[98:99] offset:64
	s_add_u32 s98, s98, 0x2200
	s_addc_u32 s99, s99, 0
	v_add_f32_e32 v136, v56, v132
	v_add_f32_e32 v137, v40, v130
	v_cvt_pk_bf16_f32 v136, v136, s0
	v_cvt_pk_bf16_f32 v137, v137, s0
	global_store_short v135, v136, s[98:99]
	global_store_short v135, v137, s[98:99] offset:64
	s_add_u32 s98, s98, 0x2200
	s_addc_u32 s99, s99, 0
	v_add_f32_e32 v136, v57, v132
	v_add_f32_e32 v137, v41, v130
	v_cvt_pk_bf16_f32 v136, v136, s0
	v_cvt_pk_bf16_f32 v137, v137, s0
	global_store_short v135, v136, s[98:99]
	global_store_short v135, v137, s[98:99] offset:64
	s_add_u32 s98, s98, 0xaa00
	s_addc_u32 s99, s99, 0
	v_add_f32_e32 v136, v58, v132
	v_add_f32_e32 v137, v42, v130
	v_cvt_pk_bf16_f32 v136, v136, s0
	v_cvt_pk_bf16_f32 v137, v137, s0
	global_store_short v135, v136, s[98:99]
	global_store_short v135, v137, s[98:99] offset:64
	s_add_u32 s98, s98, 0x2200
	s_addc_u32 s99, s99, 0
	v_add_f32_e32 v136, v59, v132
	v_add_f32_e32 v137, v43, v130
	v_cvt_pk_bf16_f32 v136, v136, s0
	v_cvt_pk_bf16_f32 v137, v137, s0
	global_store_short v135, v136, s[98:99]
	global_store_short v135, v137, s[98:99] offset:64
	s_add_u32 s98, s98, 0x2200
	s_addc_u32 s99, s99, 0
	v_add_f32_e32 v136, v60, v132
	v_add_f32_e32 v137, v44, v130
	v_cvt_pk_bf16_f32 v136, v136, s0
	v_cvt_pk_bf16_f32 v137, v137, s0
	global_store_short v135, v136, s[98:99]
	global_store_short v135, v137, s[98:99] offset:64
	s_add_u32 s98, s98, 0x2200
	s_addc_u32 s99, s99, 0
	v_add_f32_e32 v136, v61, v132
	v_add_f32_e32 v137, v45, v130
	v_cvt_pk_bf16_f32 v136, v136, s0
	v_cvt_pk_bf16_f32 v137, v137, s0
	global_store_short v135, v136, s[98:99]
	global_store_short v135, v137, s[98:99] offset:64
	s_add_u32 s98, s98, 0xaa00
	s_addc_u32 s99, s99, 0
	v_add_f32_e32 v136, v62, v132
	v_add_f32_e32 v137, v46, v130
	v_cvt_pk_bf16_f32 v136, v136, s0
	v_cvt_pk_bf16_f32 v137, v137, s0
	global_store_short v135, v136, s[98:99]
	global_store_short v135, v137, s[98:99] offset:64
	s_add_u32 s98, s98, 0x2200
	s_addc_u32 s99, s99, 0
	v_add_f32_e32 v136, v63, v132
	v_add_f32_e32 v137, v47, v130
	v_cvt_pk_bf16_f32 v136, v136, s0
	v_cvt_pk_bf16_f32 v137, v137, s0
	global_store_short v135, v136, s[98:99]
	global_store_short v135, v137, s[98:99] offset:64
	s_add_u32 s98, s98, 0x2200
	s_addc_u32 s99, s99, 0
	v_add_f32_e32 v136, v64, v132
	v_add_f32_e32 v137, v48, v130
	v_cvt_pk_bf16_f32 v136, v136, s0
	v_cvt_pk_bf16_f32 v137, v137, s0
	global_store_short v135, v136, s[98:99]
	global_store_short v135, v137, s[98:99] offset:64
	s_add_u32 s98, s98, 0x2200
	s_addc_u32 s99, s99, 0
	v_add_f32_e32 v136, v65, v132
	v_add_f32_e32 v137, v49, v130
	v_cvt_pk_bf16_f32 v136, v136, s0
	v_cvt_pk_bf16_f32 v137, v137, s0
	global_store_short v135, v136, s[98:99]
	global_store_short v135, v137, s[98:99] offset:64
	s_add_u32 s98, s98, 0xaa00
	s_addc_u32 s99, s99, 0
	v_add_f32_e32 v136, v18, v132
	v_add_f32_e32 v137, v2, v130
	v_cvt_pk_bf16_f32 v136, v136, s0
	v_cvt_pk_bf16_f32 v137, v137, s0
	global_store_short v135, v136, s[98:99]
	global_store_short v135, v137, s[98:99] offset:64
	s_add_u32 s98, s98, 0x2200
	s_addc_u32 s99, s99, 0
	v_add_f32_e32 v136, v19, v132
	v_add_f32_e32 v137, v3, v130
	v_cvt_pk_bf16_f32 v136, v136, s0
	v_cvt_pk_bf16_f32 v137, v137, s0
	global_store_short v135, v136, s[98:99]
	global_store_short v135, v137, s[98:99] offset:64
	s_add_u32 s98, s98, 0x2200
	s_addc_u32 s99, s99, 0
	v_add_f32_e32 v136, v20, v132
	v_add_f32_e32 v137, v4, v130
	v_cvt_pk_bf16_f32 v136, v136, s0
	v_cvt_pk_bf16_f32 v137, v137, s0
	global_store_short v135, v136, s[98:99]
	global_store_short v135, v137, s[98:99] offset:64
	s_add_u32 s98, s98, 0x2200
	s_addc_u32 s99, s99, 0
	v_add_f32_e32 v136, v21, v132
	v_add_f32_e32 v137, v5, v130
	v_cvt_pk_bf16_f32 v136, v136, s0
	v_cvt_pk_bf16_f32 v137, v137, s0
	global_store_short v135, v136, s[98:99]
	global_store_short v135, v137, s[98:99] offset:64
	s_add_u32 s98, s98, 0xaa00
	s_addc_u32 s99, s99, 0
	v_add_f32_e32 v136, v22, v132
	v_add_f32_e32 v137, v6, v130
	v_cvt_pk_bf16_f32 v136, v136, s0
	v_cvt_pk_bf16_f32 v137, v137, s0
	global_store_short v135, v136, s[98:99]
	global_store_short v135, v137, s[98:99] offset:64
	s_add_u32 s98, s98, 0x2200
	s_addc_u32 s99, s99, 0
	v_add_f32_e32 v136, v23, v132
	v_add_f32_e32 v137, v7, v130
	v_cvt_pk_bf16_f32 v136, v136, s0
	v_cvt_pk_bf16_f32 v137, v137, s0
; DI u16 f2bf(float x) { return (u16)(pack2(x, 0.f) & 0xffffu); }
; DI int crow(int i, int h) { return (i & 3) + 8 * (i >> 2) + 4 * h; }
; DI void phase_m1(const Params& p, int l, int grp, char* smem) {
;     ...
;       for (int ms = 0; ms < 4; ++ms)
; #pragma unroll
;         for (int ns = 0; ns < 2; ++ns)
; #pragma unroll
;           for (int i = 0; i < 16; ++i) {
;             const int row = mt * 256 + wm * 128 + ms * 32 + crow(i, lh);
;             float v = acc[ms][ns][i] + (ns ? bias1 : bias0);
;             if (rope32 && ns == 0) {
;               const float pr = __shfl_xor(v, 16);
;               const float2 cs = t32[(row & 4095) * 16 + (lr & 15)];
;               v = (lr < 16) ? (v * cs.x - pr * cs.y) : (pr * cs.y + v * cs.x);
;             }
;             z[(size_t)row * ZW + cb0 + ns * 32 + lr] = f2bf(v);
	global_store_short v135, v136, s[98:99]
	global_store_short v135, v137, s[98:99] offset:64
	s_add_u32 s98, s98, 0x2200
	s_addc_u32 s99, s99, 0
	v_add_f32_e32 v136, v24, v132
	v_add_f32_e32 v137, v8, v130
	v_cvt_pk_bf16_f32 v136, v136, s0
	v_cvt_pk_bf16_f32 v137, v137, s0
	global_store_short v135, v136, s[98:99]
	global_store_short v135, v137, s[98:99] offset:64
	s_add_u32 s98, s98, 0x2200
	s_addc_u32 s99, s99, 0
	v_add_f32_e32 v136, v25, v132
	v_add_f32_e32 v137, v9, v130
	v_cvt_pk_bf16_f32 v136, v136, s0
	v_cvt_pk_bf16_f32 v137, v137, s0
	global_store_short v135, v136, s[98:99]
	global_store_short v135, v137, s[98:99] offset:64
	s_add_u32 s98, s98, 0xaa00
	s_addc_u32 s99, s99, 0
	v_add_f32_e32 v136, v26, v132
	v_add_f32_e32 v137, v10, v130
	v_cvt_pk_bf16_f32 v136, v136, s0
	v_cvt_pk_bf16_f32 v137, v137, s0
	global_store_short v135, v136, s[98:99]
	global_store_short v135, v137, s[98:99] offset:64
	s_add_u32 s98, s98, 0x2200
	s_addc_u32 s99, s99, 0
	v_add_f32_e32 v136, v27, v132
	v_add_f32_e32 v137, v11, v130
	v_cvt_pk_bf16_f32 v136, v136, s0
	v_cvt_pk_bf16_f32 v137, v137, s0
	global_store_short v135, v136, s[98:99]
	global_store_short v135, v137, s[98:99] offset:64
	s_add_u32 s98, s98, 0x2200
	s_addc_u32 s99, s99, 0
	v_add_f32_e32 v136, v28, v132
	v_add_f32_e32 v137, v12, v130
	v_cvt_pk_bf16_f32 v136, v136, s0
	v_cvt_pk_bf16_f32 v137, v137, s0
	global_store_short v135, v136, s[98:99]
	global_store_short v135, v137, s[98:99] offset:64
	s_add_u32 s98, s98, 0x2200
	s_addc_u32 s99, s99, 0
	v_add_f32_e32 v136, v29, v132
	v_add_f32_e32 v137, v13, v130
	v_cvt_pk_bf16_f32 v136, v136, s0
	v_cvt_pk_bf16_f32 v137, v137, s0
	global_store_short v135, v136, s[98:99]
	global_store_short v135, v137, s[98:99] offset:64
	s_add_u32 s98, s98, 0xaa00
	s_addc_u32 s99, s99, 0
	v_add_f32_e32 v136, v30, v132
	v_add_f32_e32 v137, v14, v130
	v_cvt_pk_bf16_f32 v136, v136, s0
	v_cvt_pk_bf16_f32 v137, v137, s0
	global_store_short v135, v136, s[98:99]
	global_store_short v135, v137, s[98:99] offset:64
	s_add_u32 s98, s98, 0x2200
	s_addc_u32 s99, s99, 0
	v_add_f32_e32 v136, v31, v132
	v_add_f32_e32 v137, v15, v130
	v_cvt_pk_bf16_f32 v136, v136, s0
	v_cvt_pk_bf16_f32 v137, v137, s0
	global_store_short v135, v136, s[98:99]
	global_store_short v135, v137, s[98:99] offset:64
	s_add_u32 s98, s98, 0x2200
	s_addc_u32 s99, s99, 0
	v_add_f32_e32 v136, v32, v132
	v_add_f32_e32 v137, v16, v130
	v_cvt_pk_bf16_f32 v136, v136, s0
	v_cvt_pk_bf16_f32 v137, v137, s0
	global_store_short v135, v136, s[98:99]
	global_store_short v135, v137, s[98:99] offset:64
	s_add_u32 s98, s98, 0x2200
	s_addc_u32 s99, s99, 0
	v_add_f32_e32 v136, v33, v132
	v_add_f32_e32 v137, v17, v130
	v_cvt_pk_bf16_f32 v136, v136, s0
	v_cvt_pk_bf16_f32 v137, v137, s0
	global_store_short v135, v136, s[98:99]
	global_store_short v135, v137, s[98:99] offset:64
	s_andn2_b64 s[24:25], s[24:25], exec
	s_branch .LBB0_774
.Lm1_rope32_fast:
	s_lshl_b32 s6, s39, 8
	v_lshl_add_u32 v0, v168, 7, s6
	v_lshl_or_b32 v161, v167, 2, v0
	v_and_b32_e32 v160, 15, v133
	v_cmp_gt_u32_e32 vcc, 16, v131
	v_xor_b32_e32 v163, 16, v207
	v_lshlrev_b32_e32 v163, 2, v163
	v_add_u32_e32 v134, v169, v131
	v_lshlrev_b32_e32 v134, 1, v134
	v_mad_u32_u24 v164, v161, s82, v134
	s_mov_b64 s[98:99], s[44:45]
	s_waitcnt vmcnt(0)
	v_add_f32_e32 v144, v114, v132
	v_add_f32_e32 v145, v115, v132
	v_add_f32_e32 v146, v116, v132
	v_add_f32_e32 v147, v117, v132
	v_add_f32_e32 v148, v118, v132
	v_add_f32_e32 v149, v119, v132
	v_add_f32_e32 v150, v120, v132
	v_add_f32_e32 v151, v121, v132
	v_lshlrev_b32_e32 v162, 4, v161
	v_and_b32_e32 v162, 0xf840, v162
	v_or_b32_e32 v162, v162, v160
	v_lshlrev_b32_e32 v162, 3, v162
	global_load_dwordx2 v[170:171], v162, s[12:13]
	ds_bpermute_b32 v152, v163, v144
	v_or_b32_e32 v162, 1, v161
	v_lshlrev_b32_e32 v162, 4, v162
	v_and_b32_e32 v162, 0xf850, v162
	v_or_b32_e32 v162, v162, v160
	v_lshlrev_b32_e32 v162, 3, v162
	global_load_dwordx2 v[172:173], v162, s[12:13]
	ds_bpermute_b32 v153, v163, v145
	v_or_b32_e32 v162, 2, v161
	v_lshlrev_b32_e32 v162, 4, v162
	v_and_b32_e32 v162, 0xf860, v162
	v_or_b32_e32 v162, v162, v160
	v_lshlrev_b32_e32 v162, 3, v162
	global_load_dwordx2 v[174:175], v162, s[12:13]
	ds_bpermute_b32 v154, v163, v146
	v_or_b32_e32 v162, 3, v161
	v_lshlrev_b32_e32 v162, 4, v162
	v_and_b32_e32 v162, 0xf870, v162
	v_or_b32_e32 v162, v162, v160
	v_lshlrev_b32_e32 v162, 3, v162
	global_load_dwordx2 v[176:177], v162, s[12:13]
	ds_bpermute_b32 v155, v163, v147
	v_or_b32_e32 v162, 8, v161
	v_lshlrev_b32_e32 v162, 4, v162
	v_and_b32_e32 v162, 0xf8c0, v162
	v_or_b32_e32 v162, v162, v160
	v_lshlrev_b32_e32 v162, 3, v162
	global_load_dwordx2 v[178:179], v162, s[12:13]
	ds_bpermute_b32 v156, v163, v148
	v_or_b32_e32 v162, 9, v161
	v_lshlrev_b32_e32 v162, 4, v162
	v_and_b32_e32 v162, 0xf8d0, v162
	v_or_b32_e32 v162, v162, v160
	v_lshlrev_b32_e32 v162, 3, v162
	global_load_dwordx2 v[180:181], v162, s[12:13]
	ds_bpermute_b32 v157, v163, v149
	v_or_b32_e32 v162, 10, v161
	v_lshlrev_b32_e32 v162, 4, v162
	v_and_b32_e32 v162, 0xf8e0, v162
	v_or_b32_e32 v162, v162, v160
	v_lshlrev_b32_e32 v162, 3, v162
	global_load_dwordx2 v[182:183], v162, s[12:13]
	ds_bpermute_b32 v158, v163, v150
	v_or_b32_e32 v162, 11, v161
	v_lshlrev_b32_e32 v162, 4, v162
	v_and_b32_e32 v162, 0xf8f0, v162
	v_or_b32_e32 v162, v162, v160
	v_lshlrev_b32_e32 v162, 3, v162
	global_load_dwordx2 v[184:185], v162, s[12:13]
	ds_bpermute_b32 v159, v163, v151
	s_waitcnt vmcnt(0) lgkmcnt(0)
; DI u16 f2bf(float x) { return (u16)(pack2(x, 0.f) & 0xffffu); }
; DI int crow(int i, int h) { return (i & 3) + 8 * (i >> 2) + 4 * h; }
; DI void phase_m1(const Params& p, int l, int grp, char* smem) {
;     ...
;             const int row = mt * 256 + wm * 128 + ms * 32 + crow(i, lh);
;             float v = acc[ms][ns][i] + (ns ? bias1 : bias0);
;             if (rope32 && ns == 0) {
;               const float pr = __shfl_xor(v, 16);
;               const float2 cs = t32[(row & 4095) * 16 + (lr & 15)];
;               v = (lr < 16) ? (v * cs.x - pr * cs.y) : (pr * cs.y + v * cs.x);
;             }
;             z[(size_t)row * ZW + cb0 + ns * 32 + lr] = f2bf(v);
	v_mul_f32_e32 v152, v171, v152
	v_cndmask_b32_e64 v152, v152, -v152, vcc
	v_fmac_f32_e32 v152, v144, v170
	v_mul_f32_e32 v153, v173, v153
	v_cndmask_b32_e64 v153, v153, -v153, vcc
	v_fmac_f32_e32 v153, v145, v172
	v_mul_f32_e32 v154, v175, v154
	v_cndmask_b32_e64 v154, v154, -v154, vcc
	v_fmac_f32_e32 v154, v146, v174
	v_mul_f32_e32 v155, v177, v155
	v_cndmask_b32_e64 v155, v155, -v155, vcc
	v_fmac_f32_e32 v155, v147, v176
	v_mul_f32_e32 v156, v179, v156
	v_cndmask_b32_e64 v156, v156, -v156, vcc
	v_fmac_f32_e32 v156, v148, v178
	v_mul_f32_e32 v157, v181, v157
	v_cndmask_b32_e64 v157, v157, -v157, vcc
	v_fmac_f32_e32 v157, v149, v180
	v_mul_f32_e32 v158, v183, v158
	v_cndmask_b32_e64 v158, v158, -v158, vcc
	v_fmac_f32_e32 v158, v150, v182
	v_mul_f32_e32 v159, v185, v159
	v_cndmask_b32_e64 v159, v159, -v159, vcc
	v_fmac_f32_e32 v159, v151, v184
	v_add_f32_e32 v144, v98, v130
	v_cvt_pk_bf16_f32 v152, v152, s0
	v_cvt_pk_bf16_f32 v144, v144, s0
	global_store_short v164, v152, s[98:99]
	global_store_short v164, v144, s[98:99] offset:64
	s_add_u32 s98, s98, 0x2200
	s_addc_u32 s99, s99, 0
	v_add_f32_e32 v145, v99, v130
	v_cvt_pk_bf16_f32 v153, v153, s0
	v_cvt_pk_bf16_f32 v145, v145, s0
	global_store_short v164, v153, s[98:99]
	global_store_short v164, v145, s[98:99] offset:64
	s_add_u32 s98, s98, 0x2200
	s_addc_u32 s99, s99, 0
	v_add_f32_e32 v146, v100, v130
	v_cvt_pk_bf16_f32 v154, v154, s0
	v_cvt_pk_bf16_f32 v146, v146, s0
	global_store_short v164, v154, s[98:99]
	global_store_short v164, v146, s[98:99] offset:64
	s_add_u32 s98, s98, 0x2200
	s_addc_u32 s99, s99, 0
	v_add_f32_e32 v147, v101, v130
	v_cvt_pk_bf16_f32 v155, v155, s0
	v_cvt_pk_bf16_f32 v147, v147, s0
	global_store_short v164, v155, s[98:99]
	global_store_short v164, v147, s[98:99] offset:64
	s_add_u32 s98, s98, 0xaa00
	s_addc_u32 s99, s99, 0
	v_add_f32_e32 v148, v102, v130
	v_cvt_pk_bf16_f32 v156, v156, s0
	v_cvt_pk_bf16_f32 v148, v148, s0
	global_store_short v164, v156, s[98:99]
	global_store_short v164, v148, s[98:99] offset:64
	s_add_u32 s98, s98, 0x2200
	s_addc_u32 s99, s99, 0
	v_add_f32_e32 v149, v103, v130
	v_cvt_pk_bf16_f32 v157, v157, s0
	v_cvt_pk_bf16_f32 v149, v149, s0
	global_store_short v164, v157, s[98:99]
	global_store_short v164, v149, s[98:99] offset:64
	s_add_u32 s98, s98, 0x2200
	s_addc_u32 s99, s99, 0
	v_add_f32_e32 v150, v104, v130
	v_cvt_pk_bf16_f32 v158, v158, s0
	v_cvt_pk_bf16_f32 v150, v150, s0
	global_store_short v164, v158, s[98:99]
	global_store_short v164, v150, s[98:99] offset:64
	s_add_u32 s98, s98, 0x2200
	s_addc_u32 s99, s99, 0
	v_add_f32_e32 v151, v105, v130
	v_cvt_pk_bf16_f32 v159, v159, s0
	v_cvt_pk_bf16_f32 v151, v151, s0
	global_store_short v164, v159, s[98:99]
	global_store_short v164, v151, s[98:99] offset:64
	s_add_u32 s98, s98, 0xaa00
	s_addc_u32 s99, s99, 0
	v_add_f32_e32 v144, v122, v132
	v_add_f32_e32 v145, v123, v132
	v_add_f32_e32 v146, v124, v132
	v_add_f32_e32 v147, v125, v132
	v_add_f32_e32 v148, v126, v132
	v_add_f32_e32 v149, v127, v132
	v_add_f32_e32 v150, v128, v132
	v_add_f32_e32 v151, v129, v132
	v_or_b32_e32 v162, 16, v161
	v_lshlrev_b32_e32 v162, 4, v162
	v_and_b32_e32 v162, 0xf940, v162
	v_or_b32_e32 v162, v162, v160
	v_lshlrev_b32_e32 v162, 3, v162
	global_load_dwordx2 v[170:171], v162, s[12:13]
	ds_bpermute_b32 v152, v163, v144
	v_or_b32_e32 v162, 17, v161
	v_lshlrev_b32_e32 v162, 4, v162
	v_and_b32_e32 v162, 0xf950, v162
	v_or_b32_e32 v162, v162, v160
	v_lshlrev_b32_e32 v162, 3, v162
	global_load_dwordx2 v[172:173], v162, s[12:13]
	ds_bpermute_b32 v153, v163, v145
	v_or_b32_e32 v162, 18, v161
	v_lshlrev_b32_e32 v162, 4, v162
	v_and_b32_e32 v162, 0xf960, v162
	v_or_b32_e32 v162, v162, v160
	v_lshlrev_b32_e32 v162, 3, v162
	global_load_dwordx2 v[174:175], v162, s[12:13]
	ds_bpermute_b32 v154, v163, v146
	v_or_b32_e32 v162, 19, v161
	v_lshlrev_b32_e32 v162, 4, v162
	v_and_b32_e32 v162, 0xf970, v162
	v_or_b32_e32 v162, v162, v160
	v_lshlrev_b32_e32 v162, 3, v162
	global_load_dwordx2 v[176:177], v162, s[12:13]
	ds_bpermute_b32 v155, v163, v147
	v_or_b32_e32 v162, 24, v161
	v_lshlrev_b32_e32 v162, 4, v162
	v_and_b32_e32 v162, 0xf9c0, v162
	v_or_b32_e32 v162, v162, v160
	v_lshlrev_b32_e32 v162, 3, v162
	global_load_dwordx2 v[178:179], v162, s[12:13]
	ds_bpermute_b32 v156, v163, v148
	v_or_b32_e32 v162, 25, v161
	v_lshlrev_b32_e32 v162, 4, v162
	v_and_b32_e32 v162, 0xf9d0, v162
	v_or_b32_e32 v162, v162, v160
	v_lshlrev_b32_e32 v162, 3, v162
	global_load_dwordx2 v[180:181], v162, s[12:13]
	ds_bpermute_b32 v157, v163, v149
	v_or_b32_e32 v162, 26, v161
	v_lshlrev_b32_e32 v162, 4, v162
	v_and_b32_e32 v162, 0xf9e0, v162
	v_or_b32_e32 v162, v162, v160
	v_lshlrev_b32_e32 v162, 3, v162
	global_load_dwordx2 v[182:183], v162, s[12:13]
	ds_bpermute_b32 v158, v163, v150
	v_or_b32_e32 v162, 27, v161
	v_lshlrev_b32_e32 v162, 4, v162
	v_and_b32_e32 v162, 0xf9f0, v162
	v_or_b32_e32 v162, v162, v160
	v_lshlrev_b32_e32 v162, 3, v162
	global_load_dwordx2 v[184:185], v162, s[12:13]
	ds_bpermute_b32 v159, v163, v151
	s_waitcnt vmcnt(0) lgkmcnt(0)
; DI u16 f2bf(float x) { return (u16)(pack2(x, 0.f) & 0xffffu); }
; DI int crow(int i, int h) { return (i & 3) + 8 * (i >> 2) + 4 * h; }
; DI void phase_m1(const Params& p, int l, int grp, char* smem) {
;     ...
;             const int row = mt * 256 + wm * 128 + ms * 32 + crow(i, lh);
;             float v = acc[ms][ns][i] + (ns ? bias1 : bias0);
;             if (rope32 && ns == 0) {
;               const float pr = __shfl_xor(v, 16);
;               const float2 cs = t32[(row & 4095) * 16 + (lr & 15)];
;               v = (lr < 16) ? (v * cs.x - pr * cs.y) : (pr * cs.y + v * cs.x);
;             }
;             z[(size_t)row * ZW + cb0 + ns * 32 + lr] = f2bf(v);
	v_mul_f32_e32 v152, v171, v152
	v_cndmask_b32_e64 v152, v152, -v152, vcc
	v_fmac_f32_e32 v152, v144, v170
	v_mul_f32_e32 v153, v173, v153
	v_cndmask_b32_e64 v153, v153, -v153, vcc
	v_fmac_f32_e32 v153, v145, v172
	v_mul_f32_e32 v154, v175, v154
	v_cndmask_b32_e64 v154, v154, -v154, vcc
	v_fmac_f32_e32 v154, v146, v174
	v_mul_f32_e32 v155, v177, v155
	v_cndmask_b32_e64 v155, v155, -v155, vcc
	v_fmac_f32_e32 v155, v147, v176
	v_mul_f32_e32 v156, v179, v156
	v_cndmask_b32_e64 v156, v156, -v156, vcc
	v_fmac_f32_e32 v156, v148, v178
	v_mul_f32_e32 v157, v181, v157
	v_cndmask_b32_e64 v157, v157, -v157, vcc
	v_fmac_f32_e32 v157, v149, v180
	v_mul_f32_e32 v158, v183, v158
	v_cndmask_b32_e64 v158, v158, -v158, vcc
	v_fmac_f32_e32 v158, v150, v182
	v_mul_f32_e32 v159, v185, v159
	v_cndmask_b32_e64 v159, v159, -v159, vcc
	v_fmac_f32_e32 v159, v151, v184
	v_add_f32_e32 v144, v106, v130
	v_cvt_pk_bf16_f32 v152, v152, s0
	v_cvt_pk_bf16_f32 v144, v144, s0
	global_store_short v164, v152, s[98:99]
	global_store_short v164, v144, s[98:99] offset:64
	s_add_u32 s98, s98, 0x2200
	s_addc_u32 s99, s99, 0
	v_add_f32_e32 v145, v107, v130
	v_cvt_pk_bf16_f32 v153, v153, s0
	v_cvt_pk_bf16_f32 v145, v145, s0
	global_store_short v164, v153, s[98:99]
	global_store_short v164, v145, s[98:99] offset:64
	s_add_u32 s98, s98, 0x2200
	s_addc_u32 s99, s99, 0
	v_add_f32_e32 v146, v108, v130
	v_cvt_pk_bf16_f32 v154, v154, s0
	v_cvt_pk_bf16_f32 v146, v146, s0
	global_store_short v164, v154, s[98:99]
	global_store_short v164, v146, s[98:99] offset:64
	s_add_u32 s98, s98, 0x2200
	s_addc_u32 s99, s99, 0
	v_add_f32_e32 v147, v109, v130
	v_cvt_pk_bf16_f32 v155, v155, s0
	v_cvt_pk_bf16_f32 v147, v147, s0
	global_store_short v164, v155, s[98:99]
	global_store_short v164, v147, s[98:99] offset:64
	s_add_u32 s98, s98, 0xaa00
	s_addc_u32 s99, s99, 0
	v_add_f32_e32 v148, v110, v130
	v_cvt_pk_bf16_f32 v156, v156, s0
	v_cvt_pk_bf16_f32 v148, v148, s0
	global_store_short v164, v156, s[98:99]
	global_store_short v164, v148, s[98:99] offset:64
	s_add_u32 s98, s98, 0x2200
	s_addc_u32 s99, s99, 0
	v_add_f32_e32 v149, v111, v130
	v_cvt_pk_bf16_f32 v157, v157, s0
	v_cvt_pk_bf16_f32 v149, v149, s0
	global_store_short v164, v157, s[98:99]
	global_store_short v164, v149, s[98:99] offset:64
	s_add_u32 s98, s98, 0x2200
	s_addc_u32 s99, s99, 0
	v_add_f32_e32 v150, v112, v130
	v_cvt_pk_bf16_f32 v158, v158, s0
	v_cvt_pk_bf16_f32 v150, v150, s0
	global_store_short v164, v158, s[98:99]
	global_store_short v164, v150, s[98:99] offset:64
	s_add_u32 s98, s98, 0x2200
	s_addc_u32 s99, s99, 0
	v_add_f32_e32 v151, v113, v130
	v_cvt_pk_bf16_f32 v159, v159, s0
	v_cvt_pk_bf16_f32 v151, v151, s0
	global_store_short v164, v159, s[98:99]
	global_store_short v164, v151, s[98:99] offset:64
	s_add_u32 s98, s98, 0xaa00
	s_addc_u32 s99, s99, 0
	v_add_f32_e32 v144, v82, v132
	v_add_f32_e32 v145, v83, v132
	v_add_f32_e32 v146, v84, v132
	v_add_f32_e32 v147, v85, v132
	v_add_f32_e32 v148, v86, v132
	v_add_f32_e32 v149, v87, v132
	v_add_f32_e32 v150, v88, v132
	v_add_f32_e32 v151, v89, v132
	v_or_b32_e32 v162, 32, v161
	v_lshlrev_b32_e32 v162, 4, v162
	v_and_b32_e32 v162, 0xfa40, v162
	v_or_b32_e32 v162, v162, v160
	v_lshlrev_b32_e32 v162, 3, v162
	global_load_dwordx2 v[170:171], v162, s[12:13]
	ds_bpermute_b32 v152, v163, v144
	v_or_b32_e32 v162, 33, v161
	v_lshlrev_b32_e32 v162, 4, v162
	v_and_b32_e32 v162, 0xfa50, v162
	v_or_b32_e32 v162, v162, v160
	v_lshlrev_b32_e32 v162, 3, v162
	global_load_dwordx2 v[172:173], v162, s[12:13]
	ds_bpermute_b32 v153, v163, v145
	v_or_b32_e32 v162, 34, v161
	v_lshlrev_b32_e32 v162, 4, v162
	v_and_b32_e32 v162, 0xfa60, v162
	v_or_b32_e32 v162, v162, v160
	v_lshlrev_b32_e32 v162, 3, v162
	global_load_dwordx2 v[174:175], v162, s[12:13]
	ds_bpermute_b32 v154, v163, v146
	v_or_b32_e32 v162, 35, v161
	v_lshlrev_b32_e32 v162, 4, v162
	v_and_b32_e32 v162, 0xfa70, v162
	v_or_b32_e32 v162, v162, v160
	v_lshlrev_b32_e32 v162, 3, v162
	global_load_dwordx2 v[176:177], v162, s[12:13]
	ds_bpermute_b32 v155, v163, v147
	v_or_b32_e32 v162, 40, v161
	v_lshlrev_b32_e32 v162, 4, v162
	v_and_b32_e32 v162, 0xfac0, v162
	v_or_b32_e32 v162, v162, v160
	v_lshlrev_b32_e32 v162, 3, v162
	global_load_dwordx2 v[178:179], v162, s[12:13]
	ds_bpermute_b32 v156, v163, v148
	v_or_b32_e32 v162, 41, v161
	v_lshlrev_b32_e32 v162, 4, v162
	v_and_b32_e32 v162, 0xfad0, v162
	v_or_b32_e32 v162, v162, v160
	v_lshlrev_b32_e32 v162, 3, v162
	global_load_dwordx2 v[180:181], v162, s[12:13]
	ds_bpermute_b32 v157, v163, v149
	v_or_b32_e32 v162, 42, v161
	v_lshlrev_b32_e32 v162, 4, v162
	v_and_b32_e32 v162, 0xfae0, v162
	v_or_b32_e32 v162, v162, v160
	v_lshlrev_b32_e32 v162, 3, v162
	global_load_dwordx2 v[182:183], v162, s[12:13]
	ds_bpermute_b32 v158, v163, v150
	v_or_b32_e32 v162, 43, v161
	v_lshlrev_b32_e32 v162, 4, v162
	v_and_b32_e32 v162, 0xfaf0, v162
	v_or_b32_e32 v162, v162, v160
	v_lshlrev_b32_e32 v162, 3, v162
	global_load_dwordx2 v[184:185], v162, s[12:13]
	ds_bpermute_b32 v159, v163, v151
	s_waitcnt vmcnt(0) lgkmcnt(0)
; DI u16 f2bf(float x) { return (u16)(pack2(x, 0.f) & 0xffffu); }
; DI int crow(int i, int h) { return (i & 3) + 8 * (i >> 2) + 4 * h; }
; DI void phase_m1(const Params& p, int l, int grp, char* smem) {
;     ...
;             const int row = mt * 256 + wm * 128 + ms * 32 + crow(i, lh);
;             float v = acc[ms][ns][i] + (ns ? bias1 : bias0);
;             if (rope32 && ns == 0) {
;               const float pr = __shfl_xor(v, 16);
;               const float2 cs = t32[(row & 4095) * 16 + (lr & 15)];
;               v = (lr < 16) ? (v * cs.x - pr * cs.y) : (pr * cs.y + v * cs.x);
;             }
;             z[(size_t)row * ZW + cb0 + ns * 32 + lr] = f2bf(v);
	v_mul_f32_e32 v152, v171, v152
	v_cndmask_b32_e64 v152, v152, -v152, vcc
	v_fmac_f32_e32 v152, v144, v170
	v_mul_f32_e32 v153, v173, v153
	v_cndmask_b32_e64 v153, v153, -v153, vcc
	v_fmac_f32_e32 v153, v145, v172
	v_mul_f32_e32 v154, v175, v154
	v_cndmask_b32_e64 v154, v154, -v154, vcc
	v_fmac_f32_e32 v154, v146, v174
	v_mul_f32_e32 v155, v177, v155
	v_cndmask_b32_e64 v155, v155, -v155, vcc
	v_fmac_f32_e32 v155, v147, v176
	v_mul_f32_e32 v156, v179, v156
	v_cndmask_b32_e64 v156, v156, -v156, vcc
	v_fmac_f32_e32 v156, v148, v178
	v_mul_f32_e32 v157, v181, v157
	v_cndmask_b32_e64 v157, v157, -v157, vcc
	v_fmac_f32_e32 v157, v149, v180
	v_mul_f32_e32 v158, v183, v158
	v_cndmask_b32_e64 v158, v158, -v158, vcc
	v_fmac_f32_e32 v158, v150, v182
	v_mul_f32_e32 v159, v185, v159
	v_cndmask_b32_e64 v159, v159, -v159, vcc
	v_fmac_f32_e32 v159, v151, v184
	v_add_f32_e32 v144, v66, v130
	v_cvt_pk_bf16_f32 v152, v152, s0
	v_cvt_pk_bf16_f32 v144, v144, s0
	global_store_short v164, v152, s[98:99]
	global_store_short v164, v144, s[98:99] offset:64
	s_add_u32 s98, s98, 0x2200
	s_addc_u32 s99, s99, 0
	v_add_f32_e32 v145, v67, v130
	v_cvt_pk_bf16_f32 v153, v153, s0
	v_cvt_pk_bf16_f32 v145, v145, s0
	global_store_short v164, v153, s[98:99]
	global_store_short v164, v145, s[98:99] offset:64
	s_add_u32 s98, s98, 0x2200
	s_addc_u32 s99, s99, 0
	v_add_f32_e32 v146, v68, v130
	v_cvt_pk_bf16_f32 v154, v154, s0
	v_cvt_pk_bf16_f32 v146, v146, s0
	global_store_short v164, v154, s[98:99]
	global_store_short v164, v146, s[98:99] offset:64
	s_add_u32 s98, s98, 0x2200
	s_addc_u32 s99, s99, 0
	v_add_f32_e32 v147, v69, v130
	v_cvt_pk_bf16_f32 v155, v155, s0
	v_cvt_pk_bf16_f32 v147, v147, s0
	global_store_short v164, v155, s[98:99]
	global_store_short v164, v147, s[98:99] offset:64
	s_add_u32 s98, s98, 0xaa00
	s_addc_u32 s99, s99, 0
	v_add_f32_e32 v148, v70, v130
	v_cvt_pk_bf16_f32 v156, v156, s0
	v_cvt_pk_bf16_f32 v148, v148, s0
	global_store_short v164, v156, s[98:99]
	global_store_short v164, v148, s[98:99] offset:64
	s_add_u32 s98, s98, 0x2200
	s_addc_u32 s99, s99, 0
	v_add_f32_e32 v149, v71, v130
	v_cvt_pk_bf16_f32 v157, v157, s0
	v_cvt_pk_bf16_f32 v149, v149, s0
	global_store_short v164, v157, s[98:99]
	global_store_short v164, v149, s[98:99] offset:64
	s_add_u32 s98, s98, 0x2200
	s_addc_u32 s99, s99, 0
	v_add_f32_e32 v150, v72, v130
	v_cvt_pk_bf16_f32 v158, v158, s0
	v_cvt_pk_bf16_f32 v150, v150, s0
	global_store_short v164, v158, s[98:99]
	global_store_short v164, v150, s[98:99] offset:64
	s_add_u32 s98, s98, 0x2200
	s_addc_u32 s99, s99, 0
	v_add_f32_e32 v151, v73, v130
	v_cvt_pk_bf16_f32 v159, v159, s0
	v_cvt_pk_bf16_f32 v151, v151, s0
	global_store_short v164, v159, s[98:99]
	global_store_short v164, v151, s[98:99] offset:64
	s_add_u32 s98, s98, 0xaa00
	s_addc_u32 s99, s99, 0
	v_add_f32_e32 v144, v90, v132
	v_add_f32_e32 v145, v91, v132
	v_add_f32_e32 v146, v92, v132
	v_add_f32_e32 v147, v93, v132
	v_add_f32_e32 v148, v94, v132
	v_add_f32_e32 v149, v95, v132
	v_add_f32_e32 v150, v96, v132
	v_add_f32_e32 v151, v97, v132
	v_or_b32_e32 v162, 48, v161
	v_lshlrev_b32_e32 v162, 4, v162
	v_and_b32_e32 v162, 0xfb40, v162
	v_or_b32_e32 v162, v162, v160
	v_lshlrev_b32_e32 v162, 3, v162
	global_load_dwordx2 v[170:171], v162, s[12:13]
	ds_bpermute_b32 v152, v163, v144
	v_or_b32_e32 v162, 49, v161
	v_lshlrev_b32_e32 v162, 4, v162
	v_and_b32_e32 v162, 0xfb50, v162
	v_or_b32_e32 v162, v162, v160
	v_lshlrev_b32_e32 v162, 3, v162
	global_load_dwordx2 v[172:173], v162, s[12:13]
	ds_bpermute_b32 v153, v163, v145
	v_or_b32_e32 v162, 50, v161
	v_lshlrev_b32_e32 v162, 4, v162
	v_and_b32_e32 v162, 0xfb60, v162
	v_or_b32_e32 v162, v162, v160
	v_lshlrev_b32_e32 v162, 3, v162
	global_load_dwordx2 v[174:175], v162, s[12:13]
	ds_bpermute_b32 v154, v163, v146
	v_or_b32_e32 v162, 51, v161
	v_lshlrev_b32_e32 v162, 4, v162
	v_and_b32_e32 v162, 0xfb70, v162
	v_or_b32_e32 v162, v162, v160
	v_lshlrev_b32_e32 v162, 3, v162
	global_load_dwordx2 v[176:177], v162, s[12:13]
	ds_bpermute_b32 v155, v163, v147
	v_or_b32_e32 v162, 56, v161
	v_lshlrev_b32_e32 v162, 4, v162
	v_and_b32_e32 v162, 0xfbc0, v162
	v_or_b32_e32 v162, v162, v160
	v_lshlrev_b32_e32 v162, 3, v162
	global_load_dwordx2 v[178:179], v162, s[12:13]
	ds_bpermute_b32 v156, v163, v148
	v_or_b32_e32 v162, 57, v161
	v_lshlrev_b32_e32 v162, 4, v162
	v_and_b32_e32 v162, 0xfbd0, v162
	v_or_b32_e32 v162, v162, v160
	v_lshlrev_b32_e32 v162, 3, v162
	global_load_dwordx2 v[180:181], v162, s[12:13]
	ds_bpermute_b32 v157, v163, v149
	v_or_b32_e32 v162, 58, v161
	v_lshlrev_b32_e32 v162, 4, v162
	v_and_b32_e32 v162, 0xfbe0, v162
	v_or_b32_e32 v162, v162, v160
	v_lshlrev_b32_e32 v162, 3, v162
	global_load_dwordx2 v[182:183], v162, s[12:13]
	ds_bpermute_b32 v158, v163, v150
	v_or_b32_e32 v162, 59, v161
	v_lshlrev_b32_e32 v162, 4, v162
	v_and_b32_e32 v162, 0xfbf0, v162
	v_or_b32_e32 v162, v162, v160
	v_lshlrev_b32_e32 v162, 3, v162
	global_load_dwordx2 v[184:185], v162, s[12:13]
	ds_bpermute_b32 v159, v163, v151
	s_waitcnt vmcnt(0) lgkmcnt(0)
; DI u16 f2bf(float x) { return (u16)(pack2(x, 0.f) & 0xffffu); }
; DI int crow(int i, int h) { return (i & 3) + 8 * (i >> 2) + 4 * h; }
; DI void phase_m1(const Params& p, int l, int grp, char* smem) {
;     ...
;             const int row = mt * 256 + wm * 128 + ms * 32 + crow(i, lh);
;             float v = acc[ms][ns][i] + (ns ? bias1 : bias0);
;             if (rope32 && ns == 0) {
;               const float pr = __shfl_xor(v, 16);
;               const float2 cs = t32[(row & 4095) * 16 + (lr & 15)];
;               v = (lr < 16) ? (v * cs.x - pr * cs.y) : (pr * cs.y + v * cs.x);
;             }
;             z[(size_t)row * ZW + cb0 + ns * 32 + lr] = f2bf(v);
	v_mul_f32_e32 v152, v171, v152
	v_cndmask_b32_e64 v152, v152, -v152, vcc
	v_fmac_f32_e32 v152, v144, v170
	v_mul_f32_e32 v153, v173, v153
	v_cndmask_b32_e64 v153, v153, -v153, vcc
	v_fmac_f32_e32 v153, v145, v172
	v_mul_f32_e32 v154, v175, v154
	v_cndmask_b32_e64 v154, v154, -v154, vcc
	v_fmac_f32_e32 v154, v146, v174
	v_mul_f32_e32 v155, v177, v155
	v_cndmask_b32_e64 v155, v155, -v155, vcc
	v_fmac_f32_e32 v155, v147, v176
	v_mul_f32_e32 v156, v179, v156
	v_cndmask_b32_e64 v156, v156, -v156, vcc
	v_fmac_f32_e32 v156, v148, v178
	v_mul_f32_e32 v157, v181, v157
	v_cndmask_b32_e64 v157, v157, -v157, vcc
	v_fmac_f32_e32 v157, v149, v180
	v_mul_f32_e32 v158, v183, v158
	v_cndmask_b32_e64 v158, v158, -v158, vcc
	v_fmac_f32_e32 v158, v150, v182
	v_mul_f32_e32 v159, v185, v159
	v_cndmask_b32_e64 v159, v159, -v159, vcc
	v_fmac_f32_e32 v159, v151, v184
	v_add_f32_e32 v144, v74, v130
	v_cvt_pk_bf16_f32 v152, v152, s0
	v_cvt_pk_bf16_f32 v144, v144, s0
	global_store_short v164, v152, s[98:99]
	global_store_short v164, v144, s[98:99] offset:64
	s_add_u32 s98, s98, 0x2200
	s_addc_u32 s99, s99, 0
	v_add_f32_e32 v145, v75, v130
	v_cvt_pk_bf16_f32 v153, v153, s0
	v_cvt_pk_bf16_f32 v145, v145, s0
	global_store_short v164, v153, s[98:99]
	global_store_short v164, v145, s[98:99] offset:64
	s_add_u32 s98, s98, 0x2200
	s_addc_u32 s99, s99, 0
	v_add_f32_e32 v146, v76, v130
	v_cvt_pk_bf16_f32 v154, v154, s0
	v_cvt_pk_bf16_f32 v146, v146, s0
	global_store_short v164, v154, s[98:99]
	global_store_short v164, v146, s[98:99] offset:64
	s_add_u32 s98, s98, 0x2200
	s_addc_u32 s99, s99, 0
	v_add_f32_e32 v147, v77, v130
	v_cvt_pk_bf16_f32 v155, v155, s0
	v_cvt_pk_bf16_f32 v147, v147, s0
	global_store_short v164, v155, s[98:99]
	global_store_short v164, v147, s[98:99] offset:64
	s_add_u32 s98, s98, 0xaa00
	s_addc_u32 s99, s99, 0
	v_add_f32_e32 v148, v78, v130
	v_cvt_pk_bf16_f32 v156, v156, s0
	v_cvt_pk_bf16_f32 v148, v148, s0
	global_store_short v164, v156, s[98:99]
	global_store_short v164, v148, s[98:99] offset:64
	s_add_u32 s98, s98, 0x2200
	s_addc_u32 s99, s99, 0
	v_add_f32_e32 v149, v79, v130
	v_cvt_pk_bf16_f32 v157, v157, s0
	v_cvt_pk_bf16_f32 v149, v149, s0
	global_store_short v164, v157, s[98:99]
	global_store_short v164, v149, s[98:99] offset:64
	s_add_u32 s98, s98, 0x2200
	s_addc_u32 s99, s99, 0
	v_add_f32_e32 v150, v80, v130
	v_cvt_pk_bf16_f32 v158, v158, s0
	v_cvt_pk_bf16_f32 v150, v150, s0
	global_store_short v164, v158, s[98:99]
	global_store_short v164, v150, s[98:99] offset:64
	s_add_u32 s98, s98, 0x2200
	s_addc_u32 s99, s99, 0
	v_add_f32_e32 v151, v81, v130
	v_cvt_pk_bf16_f32 v159, v159, s0
	v_cvt_pk_bf16_f32 v151, v151, s0
	global_store_short v164, v159, s[98:99]
	global_store_short v164, v151, s[98:99] offset:64
	s_add_u32 s98, s98, 0xaa00
	s_addc_u32 s99, s99, 0
	v_add_f32_e32 v144, v50, v132
	v_add_f32_e32 v145, v51, v132
	v_add_f32_e32 v146, v52, v132
	v_add_f32_e32 v147, v53, v132
	v_add_f32_e32 v148, v54, v132
	v_add_f32_e32 v149, v55, v132
	v_add_f32_e32 v150, v56, v132
	v_add_f32_e32 v151, v57, v132
	v_or_b32_e32 v162, 64, v161
	v_lshlrev_b32_e32 v162, 4, v162
	v_and_b32_e32 v162, 0xfc40, v162
	v_or_b32_e32 v162, v162, v160
	v_lshlrev_b32_e32 v162, 3, v162
	global_load_dwordx2 v[170:171], v162, s[12:13]
	ds_bpermute_b32 v152, v163, v144
	v_or_b32_e32 v162, 65, v161
	v_lshlrev_b32_e32 v162, 4, v162
	v_and_b32_e32 v162, 0xfc50, v162
	v_or_b32_e32 v162, v162, v160
	v_lshlrev_b32_e32 v162, 3, v162
	global_load_dwordx2 v[172:173], v162, s[12:13]
	ds_bpermute_b32 v153, v163, v145
	v_or_b32_e32 v162, 66, v161
	v_lshlrev_b32_e32 v162, 4, v162
	v_and_b32_e32 v162, 0xfc60, v162
	v_or_b32_e32 v162, v162, v160
	v_lshlrev_b32_e32 v162, 3, v162
	global_load_dwordx2 v[174:175], v162, s[12:13]
	ds_bpermute_b32 v154, v163, v146
	v_or_b32_e32 v162, 67, v161
	v_lshlrev_b32_e32 v162, 4, v162
	v_and_b32_e32 v162, 0xfc70, v162
	v_or_b32_e32 v162, v162, v160
	v_lshlrev_b32_e32 v162, 3, v162
	global_load_dwordx2 v[176:177], v162, s[12:13]
	ds_bpermute_b32 v155, v163, v147
	v_or_b32_e32 v162, 72, v161
	v_lshlrev_b32_e32 v162, 4, v162
	v_and_b32_e32 v162, 0xfcc0, v162
	v_or_b32_e32 v162, v162, v160
	v_lshlrev_b32_e32 v162, 3, v162
	global_load_dwordx2 v[178:179], v162, s[12:13]
	ds_bpermute_b32 v156, v163, v148
	v_or_b32_e32 v162, 73, v161
	v_lshlrev_b32_e32 v162, 4, v162
	v_and_b32_e32 v162, 0xfcd0, v162
	v_or_b32_e32 v162, v162, v160
	v_lshlrev_b32_e32 v162, 3, v162
	global_load_dwordx2 v[180:181], v162, s[12:13]
	ds_bpermute_b32 v157, v163, v149
	v_or_b32_e32 v162, 74, v161
	v_lshlrev_b32_e32 v162, 4, v162
	v_and_b32_e32 v162, 0xfce0, v162
	v_or_b32_e32 v162, v162, v160
	v_lshlrev_b32_e32 v162, 3, v162
	global_load_dwordx2 v[182:183], v162, s[12:13]
	ds_bpermute_b32 v158, v163, v150
	v_or_b32_e32 v162, 75, v161
	v_lshlrev_b32_e32 v162, 4, v162
	v_and_b32_e32 v162, 0xfcf0, v162
	v_or_b32_e32 v162, v162, v160
	v_lshlrev_b32_e32 v162, 3, v162
	global_load_dwordx2 v[184:185], v162, s[12:13]
	ds_bpermute_b32 v159, v163, v151
	s_waitcnt vmcnt(0) lgkmcnt(0)
; DI u16 f2bf(float x) { return (u16)(pack2(x, 0.f) & 0xffffu); }
; DI int crow(int i, int h) { return (i & 3) + 8 * (i >> 2) + 4 * h; }
; DI void phase_m1(const Params& p, int l, int grp, char* smem) {
;     ...
;             const int row = mt * 256 + wm * 128 + ms * 32 + crow(i, lh);
;             float v = acc[ms][ns][i] + (ns ? bias1 : bias0);
;             if (rope32 && ns == 0) {
;               const float pr = __shfl_xor(v, 16);
;               const float2 cs = t32[(row & 4095) * 16 + (lr & 15)];
;               v = (lr < 16) ? (v * cs.x - pr * cs.y) : (pr * cs.y + v * cs.x);
;             }
;             z[(size_t)row * ZW + cb0 + ns * 32 + lr] = f2bf(v);
	v_mul_f32_e32 v152, v171, v152
	v_cndmask_b32_e64 v152, v152, -v152, vcc
	v_fmac_f32_e32 v152, v144, v170
	v_mul_f32_e32 v153, v173, v153
	v_cndmask_b32_e64 v153, v153, -v153, vcc
	v_fmac_f32_e32 v153, v145, v172
	v_mul_f32_e32 v154, v175, v154
	v_cndmask_b32_e64 v154, v154, -v154, vcc
	v_fmac_f32_e32 v154, v146, v174
	v_mul_f32_e32 v155, v177, v155
	v_cndmask_b32_e64 v155, v155, -v155, vcc
	v_fmac_f32_e32 v155, v147, v176
	v_mul_f32_e32 v156, v179, v156
	v_cndmask_b32_e64 v156, v156, -v156, vcc
	v_fmac_f32_e32 v156, v148, v178
	v_mul_f32_e32 v157, v181, v157
	v_cndmask_b32_e64 v157, v157, -v157, vcc
	v_fmac_f32_e32 v157, v149, v180
	v_mul_f32_e32 v158, v183, v158
	v_cndmask_b32_e64 v158, v158, -v158, vcc
	v_fmac_f32_e32 v158, v150, v182
	v_mul_f32_e32 v159, v185, v159
	v_cndmask_b32_e64 v159, v159, -v159, vcc
	v_fmac_f32_e32 v159, v151, v184
	v_add_f32_e32 v144, v34, v130
	v_cvt_pk_bf16_f32 v152, v152, s0
	v_cvt_pk_bf16_f32 v144, v144, s0
	global_store_short v164, v152, s[98:99]
	global_store_short v164, v144, s[98:99] offset:64
	s_add_u32 s98, s98, 0x2200
	s_addc_u32 s99, s99, 0
	v_add_f32_e32 v145, v35, v130
	v_cvt_pk_bf16_f32 v153, v153, s0
	v_cvt_pk_bf16_f32 v145, v145, s0
	global_store_short v164, v153, s[98:99]
	global_store_short v164, v145, s[98:99] offset:64
	s_add_u32 s98, s98, 0x2200
	s_addc_u32 s99, s99, 0
	v_add_f32_e32 v146, v36, v130
	v_cvt_pk_bf16_f32 v154, v154, s0
	v_cvt_pk_bf16_f32 v146, v146, s0
	global_store_short v164, v154, s[98:99]
	global_store_short v164, v146, s[98:99] offset:64
	s_add_u32 s98, s98, 0x2200
	s_addc_u32 s99, s99, 0
	v_add_f32_e32 v147, v37, v130
	v_cvt_pk_bf16_f32 v155, v155, s0
	v_cvt_pk_bf16_f32 v147, v147, s0
	global_store_short v164, v155, s[98:99]
	global_store_short v164, v147, s[98:99] offset:64
	s_add_u32 s98, s98, 0xaa00
	s_addc_u32 s99, s99, 0
	v_add_f32_e32 v148, v38, v130
	v_cvt_pk_bf16_f32 v156, v156, s0
	v_cvt_pk_bf16_f32 v148, v148, s0
	global_store_short v164, v156, s[98:99]
	global_store_short v164, v148, s[98:99] offset:64
	s_add_u32 s98, s98, 0x2200
	s_addc_u32 s99, s99, 0
	v_add_f32_e32 v149, v39, v130
	v_cvt_pk_bf16_f32 v157, v157, s0
	v_cvt_pk_bf16_f32 v149, v149, s0
	global_store_short v164, v157, s[98:99]
	global_store_short v164, v149, s[98:99] offset:64
	s_add_u32 s98, s98, 0x2200
	s_addc_u32 s99, s99, 0
	v_add_f32_e32 v150, v40, v130
	v_cvt_pk_bf16_f32 v158, v158, s0
	v_cvt_pk_bf16_f32 v150, v150, s0
	global_store_short v164, v158, s[98:99]
	global_store_short v164, v150, s[98:99] offset:64
	s_add_u32 s98, s98, 0x2200
	s_addc_u32 s99, s99, 0
	v_add_f32_e32 v151, v41, v130
	v_cvt_pk_bf16_f32 v159, v159, s0
	v_cvt_pk_bf16_f32 v151, v151, s0
	global_store_short v164, v159, s[98:99]
	global_store_short v164, v151, s[98:99] offset:64
	s_add_u32 s98, s98, 0xaa00
	s_addc_u32 s99, s99, 0
	v_add_f32_e32 v144, v58, v132
	v_add_f32_e32 v145, v59, v132
	v_add_f32_e32 v146, v60, v132
	v_add_f32_e32 v147, v61, v132
	v_add_f32_e32 v148, v62, v132
	v_add_f32_e32 v149, v63, v132
	v_add_f32_e32 v150, v64, v132
	v_add_f32_e32 v151, v65, v132
	v_or_b32_e32 v162, 80, v161
	v_lshlrev_b32_e32 v162, 4, v162
	v_and_b32_e32 v162, 0xfd40, v162
	v_or_b32_e32 v162, v162, v160
	v_lshlrev_b32_e32 v162, 3, v162
	global_load_dwordx2 v[170:171], v162, s[12:13]
	ds_bpermute_b32 v152, v163, v144
	v_or_b32_e32 v162, 81, v161
	v_lshlrev_b32_e32 v162, 4, v162
	v_and_b32_e32 v162, 0xfd50, v162
	v_or_b32_e32 v162, v162, v160
	v_lshlrev_b32_e32 v162, 3, v162
	global_load_dwordx2 v[172:173], v162, s[12:13]
	ds_bpermute_b32 v153, v163, v145
	v_or_b32_e32 v162, 82, v161
	v_lshlrev_b32_e32 v162, 4, v162
	v_and_b32_e32 v162, 0xfd60, v162
	v_or_b32_e32 v162, v162, v160
	v_lshlrev_b32_e32 v162, 3, v162
	global_load_dwordx2 v[174:175], v162, s[12:13]
	ds_bpermute_b32 v154, v163, v146
	v_or_b32_e32 v162, 83, v161
	v_lshlrev_b32_e32 v162, 4, v162
	v_and_b32_e32 v162, 0xfd70, v162
	v_or_b32_e32 v162, v162, v160
	v_lshlrev_b32_e32 v162, 3, v162
	global_load_dwordx2 v[176:177], v162, s[12:13]
	ds_bpermute_b32 v155, v163, v147
	v_or_b32_e32 v162, 88, v161
	v_lshlrev_b32_e32 v162, 4, v162
	v_and_b32_e32 v162, 0xfdc0, v162
	v_or_b32_e32 v162, v162, v160
	v_lshlrev_b32_e32 v162, 3, v162
	global_load_dwordx2 v[178:179], v162, s[12:13]
	ds_bpermute_b32 v156, v163, v148
	v_or_b32_e32 v162, 89, v161
	v_lshlrev_b32_e32 v162, 4, v162
	v_and_b32_e32 v162, 0xfdd0, v162
	v_or_b32_e32 v162, v162, v160
	v_lshlrev_b32_e32 v162, 3, v162
	global_load_dwordx2 v[180:181], v162, s[12:13]
	ds_bpermute_b32 v157, v163, v149
	v_or_b32_e32 v162, 90, v161
	v_lshlrev_b32_e32 v162, 4, v162
	v_and_b32_e32 v162, 0xfde0, v162
	v_or_b32_e32 v162, v162, v160
	v_lshlrev_b32_e32 v162, 3, v162
	global_load_dwordx2 v[182:183], v162, s[12:13]
	ds_bpermute_b32 v158, v163, v150
	v_or_b32_e32 v162, 91, v161
	v_lshlrev_b32_e32 v162, 4, v162
	v_and_b32_e32 v162, 0xfdf0, v162
	v_or_b32_e32 v162, v162, v160
	v_lshlrev_b32_e32 v162, 3, v162
	global_load_dwordx2 v[184:185], v162, s[12:13]
	ds_bpermute_b32 v159, v163, v151
	s_waitcnt vmcnt(0) lgkmcnt(0)
; DI u16 f2bf(float x) { return (u16)(pack2(x, 0.f) & 0xffffu); }
; DI int crow(int i, int h) { return (i & 3) + 8 * (i >> 2) + 4 * h; }
; DI void phase_m1(const Params& p, int l, int grp, char* smem) {
;     ...
;             const int row = mt * 256 + wm * 128 + ms * 32 + crow(i, lh);
;             float v = acc[ms][ns][i] + (ns ? bias1 : bias0);
;             if (rope32 && ns == 0) {
;               const float pr = __shfl_xor(v, 16);
;               const float2 cs = t32[(row & 4095) * 16 + (lr & 15)];
;               v = (lr < 16) ? (v * cs.x - pr * cs.y) : (pr * cs.y + v * cs.x);
;             }
;             z[(size_t)row * ZW + cb0 + ns * 32 + lr] = f2bf(v);
	v_mul_f32_e32 v152, v171, v152
	v_cndmask_b32_e64 v152, v152, -v152, vcc
	v_fmac_f32_e32 v152, v144, v170
	v_mul_f32_e32 v153, v173, v153
	v_cndmask_b32_e64 v153, v153, -v153, vcc
	v_fmac_f32_e32 v153, v145, v172
	v_mul_f32_e32 v154, v175, v154
	v_cndmask_b32_e64 v154, v154, -v154, vcc
	v_fmac_f32_e32 v154, v146, v174
	v_mul_f32_e32 v155, v177, v155
	v_cndmask_b32_e64 v155, v155, -v155, vcc
	v_fmac_f32_e32 v155, v147, v176
	v_mul_f32_e32 v156, v179, v156
	v_cndmask_b32_e64 v156, v156, -v156, vcc
	v_fmac_f32_e32 v156, v148, v178
	v_mul_f32_e32 v157, v181, v157
	v_cndmask_b32_e64 v157, v157, -v157, vcc
	v_fmac_f32_e32 v157, v149, v180
	v_mul_f32_e32 v158, v183, v158
	v_cndmask_b32_e64 v158, v158, -v158, vcc
	v_fmac_f32_e32 v158, v150, v182
	v_mul_f32_e32 v159, v185, v159
	v_cndmask_b32_e64 v159, v159, -v159, vcc
	v_fmac_f32_e32 v159, v151, v184
	v_add_f32_e32 v144, v42, v130
	v_cvt_pk_bf16_f32 v152, v152, s0
	v_cvt_pk_bf16_f32 v144, v144, s0
	global_store_short v164, v152, s[98:99]
	global_store_short v164, v144, s[98:99] offset:64
	s_add_u32 s98, s98, 0x2200
	s_addc_u32 s99, s99, 0
	v_add_f32_e32 v145, v43, v130
	v_cvt_pk_bf16_f32 v153, v153, s0
	v_cvt_pk_bf16_f32 v145, v145, s0
	global_store_short v164, v153, s[98:99]
	global_store_short v164, v145, s[98:99] offset:64
	s_add_u32 s98, s98, 0x2200
	s_addc_u32 s99, s99, 0
	v_add_f32_e32 v146, v44, v130
	v_cvt_pk_bf16_f32 v154, v154, s0
	v_cvt_pk_bf16_f32 v146, v146, s0
	global_store_short v164, v154, s[98:99]
	global_store_short v164, v146, s[98:99] offset:64
	s_add_u32 s98, s98, 0x2200
	s_addc_u32 s99, s99, 0
	v_add_f32_e32 v147, v45, v130
	v_cvt_pk_bf16_f32 v155, v155, s0
	v_cvt_pk_bf16_f32 v147, v147, s0
	global_store_short v164, v155, s[98:99]
	global_store_short v164, v147, s[98:99] offset:64
	s_add_u32 s98, s98, 0xaa00
	s_addc_u32 s99, s99, 0
	v_add_f32_e32 v148, v46, v130
	v_cvt_pk_bf16_f32 v156, v156, s0
	v_cvt_pk_bf16_f32 v148, v148, s0
	global_store_short v164, v156, s[98:99]
	global_store_short v164, v148, s[98:99] offset:64
	s_add_u32 s98, s98, 0x2200
	s_addc_u32 s99, s99, 0
	v_add_f32_e32 v149, v47, v130
	v_cvt_pk_bf16_f32 v157, v157, s0
	v_cvt_pk_bf16_f32 v149, v149, s0
	global_store_short v164, v157, s[98:99]
	global_store_short v164, v149, s[98:99] offset:64
	s_add_u32 s98, s98, 0x2200
	s_addc_u32 s99, s99, 0
	v_add_f32_e32 v150, v48, v130
	v_cvt_pk_bf16_f32 v158, v158, s0
	v_cvt_pk_bf16_f32 v150, v150, s0
	global_store_short v164, v158, s[98:99]
	global_store_short v164, v150, s[98:99] offset:64
	s_add_u32 s98, s98, 0x2200
	s_addc_u32 s99, s99, 0
	v_add_f32_e32 v151, v49, v130
	v_cvt_pk_bf16_f32 v159, v159, s0
	v_cvt_pk_bf16_f32 v151, v151, s0
	global_store_short v164, v159, s[98:99]
	global_store_short v164, v151, s[98:99] offset:64
	s_add_u32 s98, s98, 0xaa00
	s_addc_u32 s99, s99, 0
	v_add_f32_e32 v144, v18, v132
	v_add_f32_e32 v145, v19, v132
	v_add_f32_e32 v146, v20, v132
	v_add_f32_e32 v147, v21, v132
	v_add_f32_e32 v148, v22, v132
	v_add_f32_e32 v149, v23, v132
	v_add_f32_e32 v150, v24, v132
	v_add_f32_e32 v151, v25, v132
	v_or_b32_e32 v162, 96, v161
	v_lshlrev_b32_e32 v162, 4, v162
	v_and_b32_e32 v162, 0xfe40, v162
	v_or_b32_e32 v162, v162, v160
	v_lshlrev_b32_e32 v162, 3, v162
	global_load_dwordx2 v[170:171], v162, s[12:13]
	ds_bpermute_b32 v152, v163, v144
	v_or_b32_e32 v162, 97, v161
	v_lshlrev_b32_e32 v162, 4, v162
	v_and_b32_e32 v162, 0xfe50, v162
	v_or_b32_e32 v162, v162, v160
	v_lshlrev_b32_e32 v162, 3, v162
	global_load_dwordx2 v[172:173], v162, s[12:13]
	ds_bpermute_b32 v153, v163, v145
	v_or_b32_e32 v162, 98, v161
	v_lshlrev_b32_e32 v162, 4, v162
	v_and_b32_e32 v162, 0xfe60, v162
	v_or_b32_e32 v162, v162, v160
	v_lshlrev_b32_e32 v162, 3, v162
	global_load_dwordx2 v[174:175], v162, s[12:13]
	ds_bpermute_b32 v154, v163, v146
	v_or_b32_e32 v162, 99, v161
	v_lshlrev_b32_e32 v162, 4, v162
	v_and_b32_e32 v162, 0xfe70, v162
	v_or_b32_e32 v162, v162, v160
	v_lshlrev_b32_e32 v162, 3, v162
	global_load_dwordx2 v[176:177], v162, s[12:13]
	ds_bpermute_b32 v155, v163, v147
	v_or_b32_e32 v162, 104, v161
	v_lshlrev_b32_e32 v162, 4, v162
	v_and_b32_e32 v162, 0xfec0, v162
	v_or_b32_e32 v162, v162, v160
	v_lshlrev_b32_e32 v162, 3, v162
	global_load_dwordx2 v[178:179], v162, s[12:13]
	ds_bpermute_b32 v156, v163, v148
	v_or_b32_e32 v162, 105, v161
	v_lshlrev_b32_e32 v162, 4, v162
	v_and_b32_e32 v162, 0xfed0, v162
	v_or_b32_e32 v162, v162, v160
	v_lshlrev_b32_e32 v162, 3, v162
	global_load_dwordx2 v[180:181], v162, s[12:13]
	ds_bpermute_b32 v157, v163, v149
	v_or_b32_e32 v162, 106, v161
	v_lshlrev_b32_e32 v162, 4, v162
	v_and_b32_e32 v162, 0xfee0, v162
	v_or_b32_e32 v162, v162, v160
	v_lshlrev_b32_e32 v162, 3, v162
	global_load_dwordx2 v[182:183], v162, s[12:13]
	ds_bpermute_b32 v158, v163, v150
	v_or_b32_e32 v162, 107, v161
	v_lshlrev_b32_e32 v162, 4, v162
	v_and_b32_e32 v162, 0xfef0, v162
	v_or_b32_e32 v162, v162, v160
	v_lshlrev_b32_e32 v162, 3, v162
	global_load_dwordx2 v[184:185], v162, s[12:13]
	ds_bpermute_b32 v159, v163, v151
	s_waitcnt vmcnt(0) lgkmcnt(0)
; DI u16 f2bf(float x) { return (u16)(pack2(x, 0.f) & 0xffffu); }
; DI int crow(int i, int h) { return (i & 3) + 8 * (i >> 2) + 4 * h; }
; DI void phase_m1(const Params& p, int l, int grp, char* smem) {
;     ...
;             const int row = mt * 256 + wm * 128 + ms * 32 + crow(i, lh);
;             float v = acc[ms][ns][i] + (ns ? bias1 : bias0);
;             if (rope32 && ns == 0) {
;               const float pr = __shfl_xor(v, 16);
;               const float2 cs = t32[(row & 4095) * 16 + (lr & 15)];
;               v = (lr < 16) ? (v * cs.x - pr * cs.y) : (pr * cs.y + v * cs.x);
;             }
;             z[(size_t)row * ZW + cb0 + ns * 32 + lr] = f2bf(v);
	v_mul_f32_e32 v152, v171, v152
	v_cndmask_b32_e64 v152, v152, -v152, vcc
	v_fmac_f32_e32 v152, v144, v170
	v_mul_f32_e32 v153, v173, v153
	v_cndmask_b32_e64 v153, v153, -v153, vcc
	v_fmac_f32_e32 v153, v145, v172
	v_mul_f32_e32 v154, v175, v154
	v_cndmask_b32_e64 v154, v154, -v154, vcc
	v_fmac_f32_e32 v154, v146, v174
	v_mul_f32_e32 v155, v177, v155
	v_cndmask_b32_e64 v155, v155, -v155, vcc
	v_fmac_f32_e32 v155, v147, v176
	v_mul_f32_e32 v156, v179, v156
	v_cndmask_b32_e64 v156, v156, -v156, vcc
	v_fmac_f32_e32 v156, v148, v178
	v_mul_f32_e32 v157, v181, v157
	v_cndmask_b32_e64 v157, v157, -v157, vcc
	v_fmac_f32_e32 v157, v149, v180
	v_mul_f32_e32 v158, v183, v158
	v_cndmask_b32_e64 v158, v158, -v158, vcc
	v_fmac_f32_e32 v158, v150, v182
	v_mul_f32_e32 v159, v185, v159
	v_cndmask_b32_e64 v159, v159, -v159, vcc
	v_fmac_f32_e32 v159, v151, v184
	v_add_f32_e32 v144, v2, v130
	v_cvt_pk_bf16_f32 v152, v152, s0
	v_cvt_pk_bf16_f32 v144, v144, s0
	global_store_short v164, v152, s[98:99]
	global_store_short v164, v144, s[98:99] offset:64
	s_add_u32 s98, s98, 0x2200
	s_addc_u32 s99, s99, 0
	v_add_f32_e32 v145, v3, v130
	v_cvt_pk_bf16_f32 v153, v153, s0
	v_cvt_pk_bf16_f32 v145, v145, s0
	global_store_short v164, v153, s[98:99]
	global_store_short v164, v145, s[98:99] offset:64
	s_add_u32 s98, s98, 0x2200
	s_addc_u32 s99, s99, 0
	v_add_f32_e32 v146, v4, v130
	v_cvt_pk_bf16_f32 v154, v154, s0
	v_cvt_pk_bf16_f32 v146, v146, s0
	global_store_short v164, v154, s[98:99]
	global_store_short v164, v146, s[98:99] offset:64
	s_add_u32 s98, s98, 0x2200
	s_addc_u32 s99, s99, 0
	v_add_f32_e32 v147, v5, v130
	v_cvt_pk_bf16_f32 v155, v155, s0
	v_cvt_pk_bf16_f32 v147, v147, s0
	global_store_short v164, v155, s[98:99]
	global_store_short v164, v147, s[98:99] offset:64
	s_add_u32 s98, s98, 0xaa00
	s_addc_u32 s99, s99, 0
	v_add_f32_e32 v148, v6, v130
	v_cvt_pk_bf16_f32 v156, v156, s0
	v_cvt_pk_bf16_f32 v148, v148, s0
	global_store_short v164, v156, s[98:99]
	global_store_short v164, v148, s[98:99] offset:64
	s_add_u32 s98, s98, 0x2200
	s_addc_u32 s99, s99, 0
	v_add_f32_e32 v149, v7, v130
	v_cvt_pk_bf16_f32 v157, v157, s0
	v_cvt_pk_bf16_f32 v149, v149, s0
	global_store_short v164, v157, s[98:99]
	global_store_short v164, v149, s[98:99] offset:64
	s_add_u32 s98, s98, 0x2200
	s_addc_u32 s99, s99, 0
	v_add_f32_e32 v150, v8, v130
	v_cvt_pk_bf16_f32 v158, v158, s0
	v_cvt_pk_bf16_f32 v150, v150, s0
	global_store_short v164, v158, s[98:99]
	global_store_short v164, v150, s[98:99] offset:64
	s_add_u32 s98, s98, 0x2200
	s_addc_u32 s99, s99, 0
	v_add_f32_e32 v151, v9, v130
	v_cvt_pk_bf16_f32 v159, v159, s0
	v_cvt_pk_bf16_f32 v151, v151, s0
	global_store_short v164, v159, s[98:99]
	global_store_short v164, v151, s[98:99] offset:64
	s_add_u32 s98, s98, 0xaa00
	s_addc_u32 s99, s99, 0
	v_add_f32_e32 v144, v26, v132
	v_add_f32_e32 v145, v27, v132
	v_add_f32_e32 v146, v28, v132
	v_add_f32_e32 v147, v29, v132
	v_add_f32_e32 v148, v30, v132
	v_add_f32_e32 v149, v31, v132
	v_add_f32_e32 v150, v32, v132
	v_add_f32_e32 v151, v33, v132
	v_or_b32_e32 v162, 112, v161
	v_lshlrev_b32_e32 v162, 4, v162
	v_and_b32_e32 v162, 0xff40, v162
	v_or_b32_e32 v162, v162, v160
	v_lshlrev_b32_e32 v162, 3, v162
	global_load_dwordx2 v[170:171], v162, s[12:13]
	ds_bpermute_b32 v152, v163, v144
	v_or_b32_e32 v162, 113, v161
	v_lshlrev_b32_e32 v162, 4, v162
	v_and_b32_e32 v162, 0xff50, v162
	v_or_b32_e32 v162, v162, v160
	v_lshlrev_b32_e32 v162, 3, v162
	global_load_dwordx2 v[172:173], v162, s[12:13]
	ds_bpermute_b32 v153, v163, v145
	v_or_b32_e32 v162, 114, v161
	v_lshlrev_b32_e32 v162, 4, v162
	v_and_b32_e32 v162, 0xff60, v162
	v_or_b32_e32 v162, v162, v160
	v_lshlrev_b32_e32 v162, 3, v162
	global_load_dwordx2 v[174:175], v162, s[12:13]
	ds_bpermute_b32 v154, v163, v146
	v_or_b32_e32 v162, 115, v161
	v_lshlrev_b32_e32 v162, 4, v162
	v_and_b32_e32 v162, 0xff70, v162
	v_or_b32_e32 v162, v162, v160
	v_lshlrev_b32_e32 v162, 3, v162
	global_load_dwordx2 v[176:177], v162, s[12:13]
	ds_bpermute_b32 v155, v163, v147
	v_or_b32_e32 v162, 120, v161
	v_lshlrev_b32_e32 v162, 4, v162
	v_and_b32_e32 v162, 0xffc0, v162
	v_or_b32_e32 v162, v162, v160
	v_lshlrev_b32_e32 v162, 3, v162
	global_load_dwordx2 v[178:179], v162, s[12:13]
	ds_bpermute_b32 v156, v163, v148
	v_or_b32_e32 v162, 121, v161
	v_lshlrev_b32_e32 v162, 4, v162
	v_and_b32_e32 v162, 0xffd0, v162
	v_or_b32_e32 v162, v162, v160
	v_lshlrev_b32_e32 v162, 3, v162
	global_load_dwordx2 v[180:181], v162, s[12:13]
	ds_bpermute_b32 v157, v163, v149
	v_or_b32_e32 v162, 122, v161
	v_lshlrev_b32_e32 v162, 4, v162
	v_and_b32_e32 v162, 0xffe0, v162
	v_or_b32_e32 v162, v162, v160
	v_lshlrev_b32_e32 v162, 3, v162
	global_load_dwordx2 v[182:183], v162, s[12:13]
	ds_bpermute_b32 v158, v163, v150
	v_or_b32_e32 v162, 123, v161
	v_lshlrev_b32_e32 v162, 4, v162
	v_and_b32_e32 v162, 0xfff0, v162
	v_or_b32_e32 v162, v162, v160
	v_lshlrev_b32_e32 v162, 3, v162
	global_load_dwordx2 v[184:185], v162, s[12:13]
	ds_bpermute_b32 v159, v163, v151
	s_waitcnt vmcnt(0) lgkmcnt(0)
; DI u16 f2bf(float x) { return (u16)(pack2(x, 0.f) & 0xffffu); }
; DI int crow(int i, int h) { return (i & 3) + 8 * (i >> 2) + 4 * h; }
; DI void phase_m1(const Params& p, int l, int grp, char* smem) {
;     ...
;             const int row = mt * 256 + wm * 128 + ms * 32 + crow(i, lh);
;             float v = acc[ms][ns][i] + (ns ? bias1 : bias0);
;             if (rope32 && ns == 0) {
;               const float pr = __shfl_xor(v, 16);
;               const float2 cs = t32[(row & 4095) * 16 + (lr & 15)];
;               v = (lr < 16) ? (v * cs.x - pr * cs.y) : (pr * cs.y + v * cs.x);
;             }
;             z[(size_t)row * ZW + cb0 + ns * 32 + lr] = f2bf(v);
	v_mul_f32_e32 v152, v171, v152
	v_cndmask_b32_e64 v152, v152, -v152, vcc
	v_fmac_f32_e32 v152, v144, v170
	v_mul_f32_e32 v153, v173, v153
	v_cndmask_b32_e64 v153, v153, -v153, vcc
	v_fmac_f32_e32 v153, v145, v172
	v_mul_f32_e32 v154, v175, v154
	v_cndmask_b32_e64 v154, v154, -v154, vcc
	v_fmac_f32_e32 v154, v146, v174
	v_mul_f32_e32 v155, v177, v155
	v_cndmask_b32_e64 v155, v155, -v155, vcc
	v_fmac_f32_e32 v155, v147, v176
	v_mul_f32_e32 v156, v179, v156
	v_cndmask_b32_e64 v156, v156, -v156, vcc
	v_fmac_f32_e32 v156, v148, v178
	v_mul_f32_e32 v157, v181, v157
	v_cndmask_b32_e64 v157, v157, -v157, vcc
	v_fmac_f32_e32 v157, v149, v180
	v_mul_f32_e32 v158, v183, v158
	v_cndmask_b32_e64 v158, v158, -v158, vcc
	v_fmac_f32_e32 v158, v150, v182
	v_mul_f32_e32 v159, v185, v159
	v_cndmask_b32_e64 v159, v159, -v159, vcc
	v_fmac_f32_e32 v159, v151, v184
	v_add_f32_e32 v144, v10, v130
	v_cvt_pk_bf16_f32 v152, v152, s0
	v_cvt_pk_bf16_f32 v144, v144, s0
	global_store_short v164, v152, s[98:99]
	global_store_short v164, v144, s[98:99] offset:64
	s_add_u32 s98, s98, 0x2200
	s_addc_u32 s99, s99, 0
	v_add_f32_e32 v145, v11, v130
	v_cvt_pk_bf16_f32 v153, v153, s0
	v_cvt_pk_bf16_f32 v145, v145, s0
	global_store_short v164, v153, s[98:99]
	global_store_short v164, v145, s[98:99] offset:64
	s_add_u32 s98, s98, 0x2200
	s_addc_u32 s99, s99, 0
	v_add_f32_e32 v146, v12, v130
	v_cvt_pk_bf16_f32 v154, v154, s0
	v_cvt_pk_bf16_f32 v146, v146, s0
	global_store_short v164, v154, s[98:99]
	global_store_short v164, v146, s[98:99] offset:64
	s_add_u32 s98, s98, 0x2200
	s_addc_u32 s99, s99, 0
	v_add_f32_e32 v147, v13, v130
	v_cvt_pk_bf16_f32 v155, v155, s0
	v_cvt_pk_bf16_f32 v147, v147, s0
	global_store_short v164, v155, s[98:99]
	global_store_short v164, v147, s[98:99] offset:64
	s_add_u32 s98, s98, 0xaa00
	s_addc_u32 s99, s99, 0
	v_add_f32_e32 v148, v14, v130
	v_cvt_pk_bf16_f32 v156, v156, s0
	v_cvt_pk_bf16_f32 v148, v148, s0
	global_store_short v164, v156, s[98:99]
	global_store_short v164, v148, s[98:99] offset:64
	s_add_u32 s98, s98, 0x2200
	s_addc_u32 s99, s99, 0
	v_add_f32_e32 v149, v15, v130
	v_cvt_pk_bf16_f32 v157, v157, s0
	v_cvt_pk_bf16_f32 v149, v149, s0
	global_store_short v164, v157, s[98:99]
	global_store_short v164, v149, s[98:99] offset:64
	s_add_u32 s98, s98, 0x2200
	s_addc_u32 s99, s99, 0
	v_add_f32_e32 v150, v16, v130
	v_cvt_pk_bf16_f32 v158, v158, s0
	v_cvt_pk_bf16_f32 v150, v150, s0
	global_store_short v164, v158, s[98:99]
	global_store_short v164, v150, s[98:99] offset:64
	s_add_u32 s98, s98, 0x2200
	s_addc_u32 s99, s99, 0
	v_add_f32_e32 v151, v17, v130
	v_cvt_pk_bf16_f32 v159, v159, s0
	v_cvt_pk_bf16_f32 v151, v151, s0
	global_store_short v164, v159, s[98:99]
	global_store_short v164, v151, s[98:99] offset:64
	s_andn2_b64 s[24:25], s[24:25], exec
